# tkln
# speedup vs baseline: 1.0073x; 1.0004x over previous
; DEVI void ph_lnrouter(const Params& p, int layer, char* shm) {
;     ...
;   const int tid = opaque_tid(), w = tid >> 6, lane = tid & 63;
;   __syncthreads();
;   for (int i = tid; i < 4096; i += NTHR) {
;     float4 v = *reinterpret_cast<const float4*>(wrt + (size_t)i * 4);
;     int c = i >> 2, e0 = (i & 3) * 4;
;     Wt[(e0 + 0) * 1024 + c] = v.x;
;     Wt[(e0 + 1) * 1024 + c] = v.y;
;     Wt[(e0 + 2) * 1024 + c] = v.z;
;     Wt[(e0 + 3) * 1024 + c] = v.w;
;   }
;   __syncthreads();
;   for (int it = blockIdx.x; it < 4096; it += gridDim.x) {
;     asm volatile("" ::: "memory");
;     const int tok = it * 8 + w;
;     float x[16];
; #pragma unroll
;     for (int i = 0; i < 4; ++i) {
;       float4 v = *reinterpret_cast<const float4*>(h32 + (size_t)tok * 1024 + i * 256 + lane * 4);
;       x[i * 4] = v.x; x[i * 4 + 1] = v.y; x[i * 4 + 2] = v.z; x[i * 4 + 3] = v.w;
.LBB0_1069:
	s_or_b64 exec, exec, s[0:1]
	s_add_u32 s46, s72, 0x10e90000
	s_addc_u32 s47, s73, 0
	s_cmpk_lt_i32 s89, 0x1000
	s_cselect_b64 s[0:1], -1, 0
	s_cmpk_gt_i32 s89, 0xfff
	s_waitcnt lgkmcnt(0)
	s_barrier
	s_cbranch_scc1 .LBB0_1076
	s_waitcnt vmcnt(0)
	v_and_b32_e32 v6, 63, v0
	v_mov_b32_e32 v3, 0
	v_readlane_b32 s4, v242, 0
	v_lshlrev_b32_e32 v4, 4, v6
	v_mov_b32_e32 v5, v3
	v_readlane_b32 s5, v242, 1
	v_readlane_b32 s6, v242, 2
	v_readlane_b32 s7, v242, 3
	v_readlane_b32 s8, v242, 4
	v_readlane_b32 s9, v242, 5
	v_readlane_b32 s10, v242, 6
	v_readlane_b32 s11, v242, 7
	v_lshlrev_b32_e32 v2, 2, v6
	v_lshl_add_u64 v[50:51], s[76:77], 0, v[2:3]
	v_lshl_add_u64 v[44:45], s[10:11], 0, v[4:5]
	v_readlane_b32 s4, v242, 10
	v_readlane_b32 s6, v242, 12
	v_readlane_b32 s7, v242, 13
	v_and_b32_e32 v2, 16, v0
	v_readlane_b32 s8, v242, 14
	v_readlane_b32 s9, v242, 15
	v_lshl_add_u64 v[48:49], s[6:7], 0, v[4:5]
	v_cmp_eq_u32_e64 s[6:7], 0, v2
	v_and_b32_e32 v2, 8, v0
	v_readlane_b32 s10, v242, 16
	v_readlane_b32 s11, v242, 17
	v_cmp_eq_u32_e64 s[8:9], 0, v2
	v_and_b32_e32 v2, 4, v0
	v_readlane_b32 s12, v242, 18
	v_readlane_b32 s13, v242, 19
	v_readlane_b32 s14, v242, 20
	v_cmp_eq_u32_e64 s[10:11], 0, v2
	v_and_b32_e32 v2, 3, v0
	v_mbcnt_hi_u32_b32 v59, -1, v215
	v_ashrrev_i32_e32 v1, 6, v0
	v_readlane_b32 s5, v242, 11
	v_readlane_b32 s15, v242, 21
	v_readlane_b32 s18, v242, 24
	v_readlane_b32 s19, v242, 25
	v_cmp_eq_u32_e64 s[12:13], 0, v2
	v_and_b32_e32 v2, 60, v0
	s_add_u32 s14, s72, 0xce10000
	v_and_b32_e32 v0, 64, v59
	v_lshl_add_u64 v[46:47], s[4:5], 0, v[4:5]
	v_cmp_eq_u32_e64 s[2:3], 0, v6
	v_add_u32_e32 v58, 0, v4
	v_cmp_gt_u32_e64 s[4:5], 32, v6
	v_lshl_add_u64 v[52:53], s[46:47], 0, v[2:3]
	s_addc_u32 s15, s73, 0
	v_lshl_add_u32 v54, s89, 3, v1
	s_lshl_b32 s18, s78, 3
	v_add_u32_e32 v60, 64, v0
	v_xor_b32_e32 v61, 32, v59
	v_xor_b32_e32 v62, 16, v59
	v_xor_b32_e32 v63, 8, v59
	v_xor_b32_e32 v64, 4, v59
	v_xor_b32_e32 v65, 2, v59
	v_xor_b32_e32 v66, 1, v59
	v_mov_b32_e32 v67, 0x3727c5ac
	s_mov_b32 s19, 0x800000
	s_mov_b32 s20, 0x3fb8aa3b
	s_mov_b32 s21, 0xc2ce8ed0
	s_mov_b32 s22, 0x42b17218
	v_mov_b32_e32 v68, 0x7f800000
	s_mov_b32 s23, s89
	v_readlane_b32 s16, v242, 22
	v_readlane_b32 s17, v242, 23
	v_ashrrev_i32_e32 v55, 31, v54
	v_lshlrev_b64 v[116:117], 12, v[54:55]
	v_lshl_add_u64 v[116:117], v[44:45], 0, v[116:117]
	global_load_dwordx4 v[100:103], v[116:117], off
	global_load_dwordx4 v[104:107], v[116:117], off offset:1024
	global_load_dwordx4 v[108:111], v[116:117], off offset:2048
	global_load_dwordx4 v[112:115], v[116:117], off offset:3072
	s_waitcnt vmcnt(0)
	s_branch .LBB0_1072

; DEVI void ln_row(float (&x)[16], const float* __restrict__ g, const float* __restrict__ b, int lane, float* mu_out = nullptr,
;                  float* rstd_out = nullptr) {
;   float s = 0.f;
; #pragma unroll
;   for (int i = 0; i < 16; ++i) s += x[i];
;   s = wave_sum(s);
;   float mu = s * (1.0f / 1024.0f);
;   float v = 0.f;
; #pragma unroll
;   for (int i = 0; i < 16; ++i) { float d = x[i] - mu; v += d * d; }
;   v = wave_sum(v);
;   float rstd = rsqrtf(v * (1.0f / 1024.0f) + 1e-5f);
; DEVI void ph_lnrouter(const Params& p, int layer, char* shm) {
;     ...
;   for (int it = blockIdx.x; it < 4096; it += gridDim.x) {
;     asm volatile("" ::: "memory");
;     const int tok = it * 8 + w;
;     float x[16];
; #pragma unroll
;     for (int i = 0; i < 4; ++i) {
;       float4 v = *reinterpret_cast<const float4*>(h32 + (size_t)tok * 1024 + i * 256 + lane * 4);
;       x[i * 4] = v.x; x[i * 4 + 1] = v.y; x[i * 4 + 2] = v.z; x[i * 4 + 3] = v.w;
;     }
;     float mu_, rstd_;
;     ln_row(x, g, b, lane, &mu_, &rstd_);
.LBB0_1072:
	v_ashrrev_i32_e32 v55, 31, v54
	s_waitcnt lgkmcnt(0)
	v_lshlrev_b64 v[0:1], 12, v[54:55]
	v_lshl_add_u64 v[0:1], v[44:45], 0, v[0:1]
	s_waitcnt vmcnt(5)
	v_mov_b32_e32 v24, v100
	v_mov_b32_e32 v25, v101
	v_mov_b32_e32 v26, v102
	v_mov_b32_e32 v27, v103
	v_mov_b32_e32 v20, v104
	v_mov_b32_e32 v21, v105
	v_mov_b32_e32 v22, v106
	v_mov_b32_e32 v23, v107
	v_mov_b32_e32 v16, v108
	v_mov_b32_e32 v17, v109
	v_mov_b32_e32 v18, v110
	v_mov_b32_e32 v19, v111
	v_mov_b32_e32 v82, v112
	v_mov_b32_e32 v83, v113
	v_mov_b32_e32 v84, v114
	v_mov_b32_e32 v85, v115
	v_cmp_lt_i32_e32 vcc, v61, v60
	s_nop 1
	v_cndmask_b32_e32 v0, v59, v61, vcc
	v_lshlrev_b32_e32 v69, 2, v0
	v_cmp_lt_i32_e32 vcc, v62, v60
	v_add_f32_e32 v0, 0, v24
	v_add_f32_e32 v0, v25, v0
	v_add_f32_e32 v0, v26, v0
	v_add_f32_e32 v0, v27, v0
	v_add_f32_e32 v0, v20, v0
	v_add_f32_e32 v0, v21, v0
	v_add_f32_e32 v0, v22, v0
	v_add_f32_e32 v0, v23, v0
	v_add_f32_e32 v0, v16, v0
	v_add_f32_e32 v0, v17, v0
	v_add_f32_e32 v0, v18, v0
	v_add_f32_e32 v0, v19, v0
	v_add_f32_e32 v0, v82, v0
	v_add_f32_e32 v0, v83, v0
	v_add_f32_e32 v0, v84, v0
	v_add_f32_e32 v0, v85, v0
	ds_bpermute_b32 v1, v69, v0
	v_cndmask_b32_e32 v2, v59, v62, vcc
	v_lshlrev_b32_e32 v71, 2, v2
	v_cmp_lt_i32_e32 vcc, v63, v60
	s_waitcnt lgkmcnt(0)
	v_add_f32_e32 v0, v0, v1
	ds_bpermute_b32 v1, v71, v0
	v_cndmask_b32_e32 v2, v59, v63, vcc
	v_lshlrev_b32_e32 v70, 2, v2
	v_cmp_lt_i32_e32 vcc, v64, v60
	s_waitcnt lgkmcnt(0)
	v_add_f32_e32 v0, v0, v1
	ds_bpermute_b32 v1, v70, v0
	v_cndmask_b32_e32 v2, v59, v64, vcc
	v_lshlrev_b32_e32 v72, 2, v2
	v_cmp_lt_i32_e32 vcc, v65, v60
	s_waitcnt lgkmcnt(0)
	v_add_f32_e32 v0, v0, v1
	ds_bpermute_b32 v1, v72, v0
	v_cndmask_b32_e32 v3, v59, v65, vcc
	v_lshlrev_b32_e32 v74, 2, v3
	v_cmp_lt_i32_e32 vcc, v66, v60
	s_waitcnt lgkmcnt(0)
	v_add_f32_e32 v8, v0, v1
	ds_bpermute_b32 v9, v74, v8
	v_cndmask_b32_e32 v2, v59, v66, vcc
	v_lshlrev_b32_e32 v73, 2, v2
	global_load_dwordx4 v[40:43], v[46:47], off
	global_load_dwordx4 v[36:39], v[46:47], off offset:1024
	global_load_dwordx4 v[0:3], v[48:49], off
	global_load_dwordx4 v[4:7], v[48:49], off offset:1024
	s_waitcnt lgkmcnt(0)
	v_add_f32_e32 v56, v8, v9
	global_load_dwordx4 v[32:35], v[46:47], off offset:2048
	global_load_dwordx4 v[28:31], v[46:47], off offset:3072
	global_load_dwordx4 v[8:11], v[48:49], off offset:2048
	global_load_dwordx4 v[12:15], v[48:49], off offset:3072
	ds_bpermute_b32 v57, v73, v56
	s_waitcnt lgkmcnt(0)
	v_add_f32_e32 v57, v56, v57
	v_fmamk_f32 v79, v57, 0xba800000, v25
	v_fmamk_f32 v80, v57, 0xba800000, v24
	v_fmamk_f32 v24, v57, 0xba800000, v18
	v_mul_f32_e32 v18, v79, v79
	v_fmamk_f32 v78, v57, 0xba800000, v26
	v_fmac_f32_e32 v18, v80, v80
	v_fmac_f32_e32 v27, 0xba800000, v57
	v_fmac_f32_e32 v18, v78, v78
	v_fmamk_f32 v77, v57, 0xba800000, v20
	v_fmac_f32_e32 v18, v27, v27
	v_fmamk_f32 v76, v57, 0xba800000, v21
	v_fmac_f32_e32 v18, v77, v77
	v_fmamk_f32 v75, v57, 0xba800000, v22
	v_fmac_f32_e32 v18, v76, v76
	v_fmac_f32_e32 v23, 0xba800000, v57
	v_fmac_f32_e32 v18, v75, v75
	v_fmamk_f32 v26, v57, 0xba800000, v16
	v_fmac_f32_e32 v18, v23, v23
	v_fmamk_f32 v25, v57, 0xba800000, v17
	v_fmac_f32_e32 v18, v26, v26
	v_mul_f32_e32 v56, 0x3a800000, v57
	v_fmac_f32_e32 v18, v25, v25
	v_fmac_f32_e32 v19, 0xba800000, v57
	v_pk_add_f32 v[20:21], v[82:83], v[56:57] op_sel_hi:[1,0] neg_lo:[0,1] neg_hi:[0,1]
	v_fmac_f32_e32 v18, v24, v24
	v_pk_mul_f32 v[82:83], v[20:21], v[20:21]
	v_fmac_f32_e32 v18, v19, v19
	v_pk_add_f32 v[16:17], v[84:85], v[56:57] op_sel_hi:[1,0] neg_lo:[0,1] neg_hi:[0,1]
	v_add_f32_e32 v18, v82, v18
	v_pk_mul_f32 v[84:85], v[16:17], v[16:17]
	v_add_f32_e32 v18, v83, v18
	v_add_f32_e32 v18, v84, v18
	v_add_f32_e32 v18, v85, v18
	ds_bpermute_b32 v22, v69, v18
	s_waitcnt lgkmcnt(0)
	v_add_f32_e32 v18, v18, v22
	ds_bpermute_b32 v22, v71, v18
	s_waitcnt lgkmcnt(0)
	v_add_f32_e32 v18, v18, v22
	ds_bpermute_b32 v22, v70, v18
	s_waitcnt lgkmcnt(0)
	v_add_f32_e32 v18, v18, v22
	ds_bpermute_b32 v22, v72, v18
	s_waitcnt lgkmcnt(0)
	v_add_f32_e32 v18, v18, v22
	ds_bpermute_b32 v22, v74, v18
	s_waitcnt lgkmcnt(0)
	v_add_f32_e32 v18, v18, v22
	ds_bpermute_b32 v22, v73, v18
	s_waitcnt lgkmcnt(0)
	v_add_f32_e32 v18, v18, v22
	v_fmamk_f32 v18, v18, 0x3a800000, v67
	v_mul_f32_e32 v22, 0x4b800000, v18
	v_cmp_gt_f32_e32 vcc, s19, v18
	s_nop 1
	v_cndmask_b32_e32 v18, v18, v22, vcc
	v_rsq_f32_e32 v18, v18
	s_nop 0
	v_mul_f32_e32 v22, 0x45800000, v18
	v_cndmask_b32_e32 v57, v18, v22, vcc
	s_and_saveexec_b64 s[16:17], s[2:3]
	s_cbranch_execz .LBB0_1074
	v_lshl_add_u64 v[82:83], v[54:55], 3, s[14:15]
	global_store_dwordx2 v[82:83], v[56:57], off
.LBB0_1074:
	s_or_b64 exec, exec, s[16:17]
	v_mul_f32_e32 v18, v80, v57
	s_waitcnt vmcnt(5)
	v_fma_f32 v18, v40, v18, v0
	v_mul_f32_e32 v0, v79, v57
	v_fma_f32 v22, v41, v0, v1
	v_mul_f32_e32 v1, v27, v57
	v_mul_f32_e32 v0, v78, v57
	v_fmac_f32_e32 v3, v43, v1
	v_mul_f32_e32 v1, v77, v57
	v_fma_f32 v0, v42, v0, v2
	s_waitcnt vmcnt(4)
	v_fma_f32 v2, v36, v1, v4
	v_mul_f32_e32 v1, v76, v57
	v_fma_f32 v4, v37, v1, v5
	v_mul_f32_e32 v5, v23, v57
	v_mul_f32_e32 v1, v75, v57
	v_fmac_f32_e32 v7, v39, v5
	v_mul_f32_e32 v5, v26, v57
	v_fma_f32 v1, v38, v1, v6
	s_waitcnt vmcnt(1)
	v_fma_f32 v6, v32, v5, v8
	v_mul_f32_e32 v5, v25, v57
	v_fma_f32 v8, v33, v5, v9
	v_mul_f32_e32 v5, v24, v57
	ds_read_b128 v[24:27], v58
	v_mul_f32_e32 v9, v19, v57
	v_fma_f32 v5, v34, v5, v10
	v_fmac_f32_e32 v11, v35, v9
	v_mul_f32_e32 v9, v20, v57
	v_mul_f32_e32 v10, v21, v57
	s_waitcnt vmcnt(0)
	s_add_i32 s98, s23, s78
	s_cmpk_lt_i32 s98, 0x1000
	s_cbranch_scc0 .Lln0_nopf
	v_add_u32_e32 v116, s18, v54
	v_ashrrev_i32_e32 v117, 31, v116
	v_lshlrev_b64 v[116:117], 12, v[116:117]
	v_lshl_add_u64 v[116:117], v[44:45], 0, v[116:117]
	global_load_dwordx4 v[100:103], v[116:117], off
	global_load_dwordx4 v[104:107], v[116:117], off offset:1024
	global_load_dwordx4 v[108:111], v[116:117], off offset:2048
	global_load_dwordx4 v[112:115], v[116:117], off offset:3072
; DEVI void ln_row(float (&x)[16], const float* __restrict__ g, const float* __restrict__ b, int lane, float* mu_out = nullptr,
;                  float* rstd_out = nullptr) {
;     ...
;     x[i * 4 + 0] = (x[i * 4 + 0] - mu) * rstd * gg.x + bb.x;
;     x[i * 4 + 1] = (x[i * 4 + 1] - mu) * rstd * gg.y + bb.y;
;     x[i * 4 + 2] = (x[i * 4 + 2] - mu) * rstd * gg.z + bb.z;
;     x[i * 4 + 3] = (x[i * 4 + 3] - mu) * rstd * gg.w + bb.w;
; DEVI void ph_lnrouter(const Params& p, int layer, char* shm) {
;     ...
;     float le[16];
; #pragma unroll
;     for (int e = 0; e < 16; ++e) {
;       float a0 = 0.f;
; #pragma unroll
;       for (int i = 0; i < 4; ++i) {
;         float4 wv = *reinterpret_cast<const float4*>(Wt + e * 1024 + i * 256 + lane * 4);
;         a0 += x[i * 4] * wv.x + x[i * 4 + 1] * wv.y + x[i * 4 + 2] * wv.z + x[i * 4 + 3] * wv.w;
;       }
;       le[e] = a0;
;     }
.Lln0_nopf:
	v_fma_f32 v9, v28, v9, v12
	v_fma_f32 v10, v29, v10, v13
	v_mul_f32_e32 v12, v16, v57
	v_mul_f32_e32 v13, v17, v57
	v_fma_f32 v12, v30, v12, v14
	v_fmac_f32_e32 v15, v13, v31
	ds_read_b128 v[28:31], v58 offset:1024
	s_waitcnt lgkmcnt(1)
	v_mul_f32_e32 v13, v22, v25
	v_fmac_f32_e32 v13, v18, v24
	v_fmac_f32_e32 v13, v0, v26
	v_fmac_f32_e32 v13, v3, v27
	ds_read_b128 v[24:27], v58 offset:2048
	s_waitcnt lgkmcnt(1)
	v_mul_f32_e32 v14, v4, v29
	v_fmac_f32_e32 v14, v2, v28
	v_fmac_f32_e32 v14, v1, v30
	v_add_f32_e32 v13, 0, v13
	v_fmac_f32_e32 v14, v7, v31
	ds_read_b128 v[28:31], v58 offset:3072
	v_add_f32_e32 v13, v13, v14
	s_waitcnt lgkmcnt(1)
	v_mul_f32_e32 v14, v8, v25
	v_fmac_f32_e32 v14, v6, v24
	v_fmac_f32_e32 v14, v5, v26
	v_fmac_f32_e32 v14, v11, v27
	ds_read_b128 v[24:27], v58 offset:4096
	v_add_f32_e32 v13, v13, v14
	s_waitcnt lgkmcnt(1)
	v_mul_f32_e32 v14, v10, v29
	v_fmac_f32_e32 v14, v9, v28
	v_fmac_f32_e32 v14, v12, v30
	v_fmac_f32_e32 v14, v15, v31
	ds_read_b128 v[28:31], v58 offset:5120
	v_add_f32_e32 v13, v13, v14
	s_waitcnt lgkmcnt(1)
	v_mul_f32_e32 v14, v22, v25
	v_fmac_f32_e32 v14, v18, v24
	v_fmac_f32_e32 v14, v0, v26
	v_fmac_f32_e32 v14, v3, v27
	ds_read_b128 v[24:27], v58 offset:6144
	s_waitcnt lgkmcnt(1)
	v_mul_f32_e32 v16, v4, v29
	v_fmac_f32_e32 v16, v2, v28
	v_fmac_f32_e32 v16, v1, v30
	v_add_f32_e32 v14, 0, v14
	v_fmac_f32_e32 v16, v7, v31
	ds_read_b128 v[28:31], v58 offset:7168
	v_add_f32_e32 v14, v14, v16
	s_waitcnt lgkmcnt(1)
	v_mul_f32_e32 v16, v8, v25
	v_fmac_f32_e32 v16, v6, v24
	v_fmac_f32_e32 v16, v5, v26
	v_fmac_f32_e32 v16, v11, v27
	ds_read_b128 v[24:27], v58 offset:8192
	v_add_f32_e32 v14, v14, v16
	s_waitcnt lgkmcnt(1)
	v_mul_f32_e32 v16, v10, v29
	v_fmac_f32_e32 v16, v9, v28
	v_fmac_f32_e32 v16, v12, v30
	v_fmac_f32_e32 v16, v15, v31
	ds_read_b128 v[28:31], v58 offset:9216
	v_add_f32_e32 v14, v14, v16
	s_waitcnt lgkmcnt(1)
	v_mul_f32_e32 v16, v22, v25
	v_fmac_f32_e32 v16, v18, v24
	v_fmac_f32_e32 v16, v0, v26
	v_fmac_f32_e32 v16, v3, v27
	ds_read_b128 v[24:27], v58 offset:10240
	s_waitcnt lgkmcnt(1)
	v_mul_f32_e32 v17, v4, v29
	v_fmac_f32_e32 v17, v2, v28
	v_fmac_f32_e32 v17, v1, v30
	v_add_f32_e32 v16, 0, v16
	v_fmac_f32_e32 v17, v7, v31
	ds_read_b128 v[28:31], v58 offset:11264
	v_add_f32_e32 v16, v16, v17
	s_waitcnt lgkmcnt(1)
	v_mul_f32_e32 v17, v8, v25
	v_fmac_f32_e32 v17, v6, v24
	v_fmac_f32_e32 v17, v5, v26
	v_fmac_f32_e32 v17, v11, v27
	ds_read_b128 v[24:27], v58 offset:12288
	v_add_f32_e32 v16, v16, v17
	s_waitcnt lgkmcnt(1)
	v_mul_f32_e32 v17, v10, v29
	v_fmac_f32_e32 v17, v9, v28
	v_fmac_f32_e32 v17, v12, v30
	v_fmac_f32_e32 v17, v15, v31
	ds_read_b128 v[28:31], v58 offset:13312
	v_add_f32_e32 v16, v16, v17
	s_waitcnt lgkmcnt(1)
	v_mul_f32_e32 v17, v22, v25
	v_fmac_f32_e32 v17, v18, v24
	v_fmac_f32_e32 v17, v0, v26
	v_fmac_f32_e32 v17, v3, v27
	ds_read_b128 v[24:27], v58 offset:14336
	s_waitcnt lgkmcnt(1)
	v_mul_f32_e32 v19, v4, v29
	v_fmac_f32_e32 v19, v2, v28
	v_fmac_f32_e32 v19, v1, v30
	v_add_f32_e32 v17, 0, v17
	v_fmac_f32_e32 v19, v7, v31
	ds_read_b128 v[28:31], v58 offset:15360
	v_add_f32_e32 v17, v17, v19
	s_waitcnt lgkmcnt(1)
	v_mul_f32_e32 v19, v8, v25
	v_fmac_f32_e32 v19, v6, v24
	v_fmac_f32_e32 v19, v5, v26
	v_fmac_f32_e32 v19, v11, v27
	ds_read_b128 v[24:27], v58 offset:16384
	v_add_f32_e32 v17, v17, v19
	s_waitcnt lgkmcnt(1)
	v_mul_f32_e32 v19, v10, v29
	v_fmac_f32_e32 v19, v9, v28
	v_fmac_f32_e32 v19, v12, v30
	v_fmac_f32_e32 v19, v15, v31
	ds_read_b128 v[28:31], v58 offset:17408
	v_add_f32_e32 v17, v17, v19
	s_waitcnt lgkmcnt(1)
	v_mul_f32_e32 v19, v22, v25
	v_fmac_f32_e32 v19, v18, v24
	v_fmac_f32_e32 v19, v0, v26
	v_fmac_f32_e32 v19, v3, v27
	ds_read_b128 v[24:27], v58 offset:18432
	s_waitcnt lgkmcnt(1)
	v_mul_f32_e32 v20, v4, v29
	v_fmac_f32_e32 v20, v2, v28
	v_fmac_f32_e32 v20, v1, v30
	v_add_f32_e32 v19, 0, v19
	v_fmac_f32_e32 v20, v7, v31
	ds_read_b128 v[28:31], v58 offset:19456
	v_add_f32_e32 v19, v19, v20
	s_waitcnt lgkmcnt(1)
	v_mul_f32_e32 v20, v8, v25
	v_fmac_f32_e32 v20, v6, v24
	v_fmac_f32_e32 v20, v5, v26
	v_fmac_f32_e32 v20, v11, v27
	ds_read_b128 v[24:27], v58 offset:20480
	v_add_f32_e32 v19, v19, v20
	s_waitcnt lgkmcnt(1)
	v_mul_f32_e32 v20, v10, v29
	v_fmac_f32_e32 v20, v9, v28
	v_fmac_f32_e32 v20, v12, v30
	v_fmac_f32_e32 v20, v15, v31
	ds_read_b128 v[28:31], v58 offset:21504
	v_add_f32_e32 v19, v19, v20
	s_waitcnt lgkmcnt(1)
	v_mul_f32_e32 v20, v22, v25
	v_fmac_f32_e32 v20, v18, v24
	v_fmac_f32_e32 v20, v0, v26
	v_fmac_f32_e32 v20, v3, v27
	ds_read_b128 v[24:27], v58 offset:22528
	s_waitcnt lgkmcnt(1)
	v_mul_f32_e32 v21, v4, v29
	v_fmac_f32_e32 v21, v2, v28
	v_fmac_f32_e32 v21, v1, v30
	v_add_f32_e32 v20, 0, v20
	v_fmac_f32_e32 v21, v7, v31
	ds_read_b128 v[28:31], v58 offset:23552
	v_add_f32_e32 v20, v20, v21
	s_waitcnt lgkmcnt(1)
	v_mul_f32_e32 v21, v8, v25
	v_fmac_f32_e32 v21, v6, v24
	v_fmac_f32_e32 v21, v5, v26
	v_fmac_f32_e32 v21, v11, v27
	ds_read_b128 v[24:27], v58 offset:24576
	v_add_f32_e32 v20, v20, v21
	s_waitcnt lgkmcnt(1)
	v_mul_f32_e32 v21, v10, v29
	v_fmac_f32_e32 v21, v9, v28
	v_fmac_f32_e32 v21, v12, v30
	v_fmac_f32_e32 v21, v15, v31
	ds_read_b128 v[28:31], v58 offset:25600
	v_add_f32_e32 v20, v20, v21
	s_waitcnt lgkmcnt(1)
	v_mul_f32_e32 v21, v22, v25
	v_fmac_f32_e32 v21, v18, v24
	v_fmac_f32_e32 v21, v0, v26
	v_fmac_f32_e32 v21, v3, v27
	ds_read_b128 v[24:27], v58 offset:26624
	s_waitcnt lgkmcnt(1)
	v_mul_f32_e32 v23, v4, v29
	v_fmac_f32_e32 v23, v2, v28
	v_fmac_f32_e32 v23, v1, v30
	v_add_f32_e32 v21, 0, v21
	v_fmac_f32_e32 v23, v7, v31
	ds_read_b128 v[28:31], v58 offset:27648
	v_add_f32_e32 v21, v21, v23
	s_waitcnt lgkmcnt(1)
; DEVI void ph_lnrouter(const Params& p, int layer, char* shm) {
;     ...
;     float le[16];
; #pragma unroll
;     for (int e = 0; e < 16; ++e) {
;       float a0 = 0.f;
; #pragma unroll
;       for (int i = 0; i < 4; ++i) {
;         float4 wv = *reinterpret_cast<const float4*>(Wt + e * 1024 + i * 256 + lane * 4);
;         a0 += x[i * 4] * wv.x + x[i * 4 + 1] * wv.y + x[i * 4 + 2] * wv.z + x[i * 4 + 3] * wv.w;
;       }
;       le[e] = a0;
;     }
	v_mul_f32_e32 v23, v8, v25
	v_fmac_f32_e32 v23, v6, v24
	v_fmac_f32_e32 v23, v5, v26
	v_fmac_f32_e32 v23, v11, v27
	v_add_f32_e32 v21, v21, v23
	s_waitcnt lgkmcnt(0)
	v_mul_f32_e32 v23, v10, v29
	ds_read_b128 v[24:27], v58 offset:28672
	v_fmac_f32_e32 v23, v9, v28
	v_fmac_f32_e32 v23, v12, v30
	v_fmac_f32_e32 v23, v15, v31
	ds_read_b128 v[28:31], v58 offset:29696
	v_add_f32_e32 v21, v21, v23
	s_waitcnt lgkmcnt(1)
	v_mul_f32_e32 v23, v22, v25
	v_fmac_f32_e32 v23, v18, v24
	v_fmac_f32_e32 v23, v0, v26
	v_fmac_f32_e32 v23, v3, v27
	s_waitcnt lgkmcnt(0)
	v_mul_f32_e32 v29, v4, v29
	ds_read_b128 v[24:27], v58 offset:30720
	v_fmac_f32_e32 v29, v2, v28
	v_fmac_f32_e32 v29, v1, v30
	v_add_f32_e32 v23, 0, v23
	v_fmac_f32_e32 v29, v7, v31
	v_add_f32_e32 v23, v23, v29
	ds_read_b128 v[28:31], v58 offset:31744
	s_waitcnt lgkmcnt(1)
	v_mul_f32_e32 v25, v8, v25
	v_fmac_f32_e32 v25, v6, v24
	v_fmac_f32_e32 v25, v5, v26
	v_fmac_f32_e32 v25, v11, v27
	v_add_f32_e32 v23, v23, v25
	s_waitcnt lgkmcnt(0)
	v_mul_f32_e32 v29, v10, v29
	ds_read_b128 v[24:27], v58 offset:32768
	v_fmac_f32_e32 v29, v9, v28
	v_fmac_f32_e32 v29, v12, v30
	v_fmac_f32_e32 v29, v15, v31
	v_add_f32_e32 v23, v23, v29
	ds_read_b128 v[28:31], v58 offset:33792
	s_waitcnt lgkmcnt(1)
	v_mul_f32_e32 v25, v22, v25
	v_fmac_f32_e32 v25, v18, v24
	v_fmac_f32_e32 v25, v0, v26
	v_fmac_f32_e32 v25, v3, v27
	v_add_f32_e32 v32, 0, v25
	s_waitcnt lgkmcnt(0)
	v_mul_f32_e32 v29, v4, v29
	ds_read_b128 v[24:27], v58 offset:34816
	v_fmac_f32_e32 v29, v2, v28
	v_fmac_f32_e32 v29, v1, v30
	v_fmac_f32_e32 v29, v7, v31
	v_add_f32_e32 v32, v32, v29
	ds_read_b128 v[28:31], v58 offset:35840
	s_waitcnt lgkmcnt(1)
	v_mul_f32_e32 v25, v8, v25
	v_fmac_f32_e32 v25, v6, v24
	v_fmac_f32_e32 v25, v5, v26
	v_fmac_f32_e32 v25, v11, v27
	v_add_f32_e32 v32, v32, v25
	s_waitcnt lgkmcnt(0)
	v_mul_f32_e32 v29, v10, v29
	ds_read_b128 v[24:27], v58 offset:36864
	v_fmac_f32_e32 v29, v9, v28
	v_fmac_f32_e32 v29, v12, v30
	v_fmac_f32_e32 v29, v15, v31
	v_add_f32_e32 v32, v32, v29
	ds_read_b128 v[28:31], v58 offset:37888
	s_waitcnt lgkmcnt(1)
	v_mul_f32_e32 v25, v22, v25
	v_fmac_f32_e32 v25, v18, v24
	v_fmac_f32_e32 v25, v0, v26
	v_fmac_f32_e32 v25, v3, v27
	v_add_f32_e32 v33, 0, v25
	s_waitcnt lgkmcnt(0)
	v_mul_f32_e32 v29, v4, v29
	ds_read_b128 v[24:27], v58 offset:38912
	v_fmac_f32_e32 v29, v2, v28
	v_fmac_f32_e32 v29, v1, v30
	v_fmac_f32_e32 v29, v7, v31
	v_add_f32_e32 v33, v33, v29
	ds_read_b128 v[28:31], v58 offset:39936
	s_waitcnt lgkmcnt(1)
	v_mul_f32_e32 v25, v8, v25
	v_fmac_f32_e32 v25, v6, v24
	v_fmac_f32_e32 v25, v5, v26
	v_fmac_f32_e32 v25, v11, v27
	v_add_f32_e32 v33, v33, v25
	s_waitcnt lgkmcnt(0)
	v_mul_f32_e32 v29, v10, v29
	ds_read_b128 v[24:27], v58 offset:40960
	v_fmac_f32_e32 v29, v9, v28
	v_fmac_f32_e32 v29, v12, v30
	v_fmac_f32_e32 v29, v15, v31
	v_add_f32_e32 v33, v33, v29
	ds_read_b128 v[28:31], v58 offset:41984
	s_waitcnt lgkmcnt(1)
	v_mul_f32_e32 v25, v22, v25
	v_fmac_f32_e32 v25, v18, v24
	v_fmac_f32_e32 v25, v0, v26
	v_fmac_f32_e32 v25, v3, v27
	v_add_f32_e32 v34, 0, v25
	s_waitcnt lgkmcnt(0)
	v_mul_f32_e32 v29, v4, v29
	ds_read_b128 v[24:27], v58 offset:43008
	v_fmac_f32_e32 v29, v2, v28
	v_fmac_f32_e32 v29, v1, v30
	v_fmac_f32_e32 v29, v7, v31
	v_add_f32_e32 v34, v34, v29
	ds_read_b128 v[28:31], v58 offset:44032
	s_waitcnt lgkmcnt(1)
	v_mul_f32_e32 v25, v8, v25
	v_fmac_f32_e32 v25, v6, v24
	v_fmac_f32_e32 v25, v5, v26
	v_fmac_f32_e32 v25, v11, v27
	v_add_f32_e32 v34, v34, v25
	s_waitcnt lgkmcnt(0)
	v_mul_f32_e32 v29, v10, v29
	ds_read_b128 v[24:27], v58 offset:45056
	v_fmac_f32_e32 v29, v9, v28
	v_fmac_f32_e32 v29, v12, v30
	v_fmac_f32_e32 v29, v15, v31
	v_add_f32_e32 v34, v34, v29
	ds_read_b128 v[28:31], v58 offset:46080
	s_waitcnt lgkmcnt(1)
	v_mul_f32_e32 v25, v22, v25
	v_fmac_f32_e32 v25, v18, v24
	v_fmac_f32_e32 v25, v0, v26
	v_fmac_f32_e32 v25, v3, v27
	v_add_f32_e32 v35, 0, v25
	s_waitcnt lgkmcnt(0)
	v_mul_f32_e32 v29, v4, v29
	ds_read_b128 v[24:27], v58 offset:47104
	v_fmac_f32_e32 v29, v2, v28
	v_fmac_f32_e32 v29, v1, v30
	v_fmac_f32_e32 v29, v7, v31
	v_add_f32_e32 v35, v35, v29
	ds_read_b128 v[28:31], v58 offset:48128
	s_waitcnt lgkmcnt(1)
	v_mul_f32_e32 v25, v8, v25
	v_fmac_f32_e32 v25, v6, v24
	v_fmac_f32_e32 v25, v5, v26
	v_fmac_f32_e32 v25, v11, v27
	v_add_f32_e32 v35, v35, v25
	s_waitcnt lgkmcnt(0)
	v_mul_f32_e32 v29, v10, v29
	ds_read_b128 v[24:27], v58 offset:49152
	v_fmac_f32_e32 v29, v9, v28
	v_fmac_f32_e32 v29, v12, v30
	v_fmac_f32_e32 v29, v15, v31
	v_add_f32_e32 v35, v35, v29
	ds_read_b128 v[28:31], v58 offset:50176
	s_waitcnt lgkmcnt(1)
	v_mul_f32_e32 v25, v22, v25
	v_fmac_f32_e32 v25, v18, v24
	v_fmac_f32_e32 v25, v0, v26
	v_fmac_f32_e32 v25, v3, v27
	v_add_f32_e32 v36, 0, v25
	s_waitcnt lgkmcnt(0)
	v_mul_f32_e32 v29, v4, v29
	ds_read_b128 v[24:27], v58 offset:51200
	v_fmac_f32_e32 v29, v2, v28
	v_fmac_f32_e32 v29, v1, v30
	v_fmac_f32_e32 v29, v7, v31
	v_add_f32_e32 v36, v36, v29
	ds_read_b128 v[28:31], v58 offset:52224
	s_waitcnt lgkmcnt(1)
	v_mul_f32_e32 v25, v8, v25
	v_fmac_f32_e32 v25, v6, v24
	v_fmac_f32_e32 v25, v5, v26
	v_fmac_f32_e32 v25, v11, v27
	v_add_f32_e32 v36, v36, v25
	s_waitcnt lgkmcnt(0)
	v_mul_f32_e32 v29, v10, v29
	ds_read_b128 v[24:27], v58 offset:53248
	v_fmac_f32_e32 v29, v9, v28
	v_fmac_f32_e32 v29, v12, v30
	v_fmac_f32_e32 v29, v15, v31
	v_add_f32_e32 v36, v36, v29
	ds_read_b128 v[28:31], v58 offset:54272
	s_waitcnt lgkmcnt(1)
	v_mul_f32_e32 v25, v22, v25
	v_fmac_f32_e32 v25, v18, v24
	v_fmac_f32_e32 v25, v0, v26
	v_fmac_f32_e32 v25, v3, v27
	v_add_f32_e32 v37, 0, v25
	s_waitcnt lgkmcnt(0)
; DEVI float reduce16(float (&v)[16], int lane) {
;   {
;     bool up = (lane & 32) != 0;
; #pragma unroll
;     for (int k = 0; k < 8; ++k) {
;       float send = up ? v[k] : v[k + 8];
;       float keep = up ? v[k + 8] : v[k];
;       v[k] = keep + __shfl_xor(send, 32);
;     }
;   }
;   {
;     bool up = (lane & 16) != 0;
; #pragma unroll
;     for (int k = 0; k < 4; ++k) {
;       float send = up ? v[k] : v[k + 4];
;       float keep = up ? v[k + 4] : v[k];
;       v[k] = keep + __shfl_xor(send, 16);
;     }
;   }
;   {
;     bool up = (lane & 8) != 0;
; #pragma unroll
;     for (int k = 0; k < 2; ++k) {
;       float send = up ? v[k] : v[k + 2];
;       float keep = up ? v[k + 2] : v[k];
;       v[k] = keep + __shfl_xor(send, 8);
;     }
;   }
;   {
;     bool up = (lane & 4) != 0;
;     float send = up ? v[0] : v[1];
;     float keep = up ? v[1] : v[0];
;     v[0] = keep + __shfl_xor(send, 4);
;   }
;   float r = v[0];
;   r += __shfl_xor(r, 2);
;   r += __shfl_xor(r, 1);
;   return r;
; }
; DEVI void ph_lnrouter(const Params& p, int layer, char* shm) {
;     ...
;       float v = reduce16(le, lane);
;       float mx = v;
;       mx = fmaxf(mx, __shfl_xor(mx, 32));
;       mx = fmaxf(mx, __shfl_xor(mx, 16));
;       mx = fmaxf(mx, __shfl_xor(mx, 8));
;       mx = fmaxf(mx, __shfl_xor(mx, 4));
;       float ex = expf(v - mx);
;       float sm = ex;
;       sm += __shfl_xor(sm, 32);
;       sm += __shfl_xor(sm, 16);
;       sm += __shfl_xor(sm, 8);
;       sm += __shfl_xor(sm, 4);
;       int e = ((lane >> 5) & 1) * 8 + ((lane >> 4) & 1) * 4 + ((lane >> 3) & 1) * 2 + ((lane >> 2) & 1);
;       if ((lane & 3) == 0) aff[(size_t)tok * 16 + e] = ex / sm;
	v_mul_f32_e32 v29, v4, v29
	ds_read_b128 v[24:27], v58 offset:55296
	v_fmac_f32_e32 v29, v2, v28
	v_fmac_f32_e32 v29, v1, v30
	v_fmac_f32_e32 v29, v7, v31
	v_add_f32_e32 v37, v37, v29
	ds_read_b128 v[28:31], v58 offset:56320
	s_waitcnt lgkmcnt(1)
	v_mul_f32_e32 v25, v8, v25
	v_fmac_f32_e32 v25, v6, v24
	v_fmac_f32_e32 v25, v5, v26
	v_fmac_f32_e32 v25, v11, v27
	v_add_f32_e32 v37, v37, v25
	s_waitcnt lgkmcnt(0)
	v_mul_f32_e32 v29, v10, v29
	ds_read_b128 v[24:27], v58 offset:57344
	v_fmac_f32_e32 v29, v9, v28
	v_fmac_f32_e32 v29, v12, v30
	v_fmac_f32_e32 v29, v15, v31
	v_add_f32_e32 v37, v37, v29
	ds_read_b128 v[28:31], v58 offset:58368
	s_waitcnt lgkmcnt(1)
	v_mul_f32_e32 v25, v22, v25
	v_fmac_f32_e32 v25, v18, v24
	v_fmac_f32_e32 v25, v0, v26
	v_fmac_f32_e32 v25, v3, v27
	v_add_f32_e32 v38, 0, v25
	s_waitcnt lgkmcnt(0)
	v_mul_f32_e32 v29, v4, v29
	ds_read_b128 v[24:27], v58 offset:59392
	v_fmac_f32_e32 v29, v2, v28
	v_fmac_f32_e32 v29, v1, v30
	v_fmac_f32_e32 v29, v7, v31
	v_add_f32_e32 v38, v38, v29
	ds_read_b128 v[28:31], v58 offset:60416
	s_waitcnt lgkmcnt(1)
	v_mul_f32_e32 v25, v8, v25
	v_fmac_f32_e32 v25, v6, v24
	v_fmac_f32_e32 v25, v5, v26
	v_fmac_f32_e32 v25, v11, v27
	v_add_f32_e32 v38, v38, v25
	s_waitcnt lgkmcnt(0)
	v_mul_f32_e32 v29, v10, v29
	ds_read_b128 v[24:27], v58 offset:61440
	v_fmac_f32_e32 v29, v9, v28
	v_fmac_f32_e32 v29, v12, v30
	v_fmac_f32_e32 v29, v15, v31
	v_add_f32_e32 v38, v38, v29
	ds_read_b128 v[28:31], v58 offset:62464
	s_waitcnt lgkmcnt(1)
	v_mul_f32_e32 v25, v22, v25
	v_fmac_f32_e32 v25, v18, v24
	v_fmac_f32_e32 v25, v0, v26
	v_fmac_f32_e32 v25, v3, v27
	v_add_f32_e32 v39, 0, v25
	s_waitcnt lgkmcnt(0)
	v_mul_f32_e32 v29, v4, v29
	ds_read_b128 v[24:27], v58 offset:63488
	v_fmac_f32_e32 v29, v2, v28
	v_fmac_f32_e32 v29, v1, v30
	v_fmac_f32_e32 v29, v7, v31
	v_add_f32_e32 v39, v39, v29
	ds_read_b128 v[28:31], v58 offset:64512
	s_waitcnt lgkmcnt(1)
	v_mul_f32_e32 v25, v8, v25
	v_fmac_f32_e32 v25, v6, v24
	v_fmac_f32_e32 v25, v5, v26
	v_fmac_f32_e32 v25, v11, v27
	v_add_f32_e32 v24, v39, v25
	s_waitcnt lgkmcnt(0)
	v_mul_f32_e32 v25, v10, v29
	v_fmac_f32_e32 v25, v9, v28
	v_fmac_f32_e32 v25, v12, v30
	v_fmac_f32_e32 v25, v15, v31
	v_add_f32_e32 v24, v24, v25
	v_cndmask_b32_e64 v25, v13, v32, s[4:5]
	v_cndmask_b32_e64 v26, v14, v33, s[4:5]
	ds_bpermute_b32 v25, v69, v25
	ds_bpermute_b32 v26, v69, v26
	v_cndmask_b32_e64 v13, v32, v13, s[4:5]
	v_cndmask_b32_e64 v14, v33, v14, s[4:5]
	v_cndmask_b32_e64 v27, v16, v34, s[4:5]
	s_waitcnt lgkmcnt(1)
	v_add_f32_e32 v13, v13, v25
	s_waitcnt lgkmcnt(0)
	v_add_f32_e32 v14, v14, v26
	v_cndmask_b32_e64 v25, v17, v35, s[4:5]
	v_cndmask_b32_e64 v26, v19, v36, s[4:5]
	ds_bpermute_b32 v27, v69, v27
	ds_bpermute_b32 v25, v69, v25
	ds_bpermute_b32 v26, v69, v26
	v_cndmask_b32_e64 v16, v34, v16, s[4:5]
	v_cndmask_b32_e64 v17, v35, v17, s[4:5]
	v_cndmask_b32_e64 v19, v36, v19, s[4:5]
	s_waitcnt lgkmcnt(2)
	v_add_f32_e32 v16, v16, v27
	v_cndmask_b32_e64 v27, v20, v37, s[4:5]
	s_waitcnt lgkmcnt(1)
	v_add_f32_e32 v17, v17, v25
	s_waitcnt lgkmcnt(0)
	v_add_f32_e32 v19, v19, v26
	v_cndmask_b32_e64 v25, v21, v38, s[4:5]
	v_cndmask_b32_e64 v26, v23, v24, s[4:5]
	ds_bpermute_b32 v27, v69, v27
	ds_bpermute_b32 v25, v69, v25
	ds_bpermute_b32 v26, v69, v26
	v_cndmask_b32_e64 v20, v37, v20, s[4:5]
	v_cndmask_b32_e64 v21, v38, v21, s[4:5]
	v_cndmask_b32_e64 v23, v24, v23, s[4:5]
	s_waitcnt lgkmcnt(2)
	v_add_f32_e32 v20, v20, v27
	s_waitcnt lgkmcnt(1)
	v_add_f32_e32 v21, v21, v25
	s_waitcnt lgkmcnt(0)
	v_add_f32_e32 v23, v23, v26
	v_cndmask_b32_e64 v27, v13, v19, s[6:7]
	v_cndmask_b32_e64 v13, v19, v13, s[6:7]
	v_cndmask_b32_e64 v19, v14, v20, s[6:7]
	v_cndmask_b32_e64 v14, v20, v14, s[6:7]
	v_cndmask_b32_e64 v20, v16, v21, s[6:7]
	v_cndmask_b32_e64 v24, v17, v23, s[6:7]
	ds_bpermute_b32 v27, v71, v27
	ds_bpermute_b32 v19, v71, v19
	ds_bpermute_b32 v20, v71, v20
	ds_bpermute_b32 v24, v71, v24
	v_cndmask_b32_e64 v16, v21, v16, s[6:7]
	v_cndmask_b32_e64 v17, v23, v17, s[6:7]
	s_waitcnt lgkmcnt(3)
	v_add_f32_e32 v13, v13, v27
	s_waitcnt lgkmcnt(2)
	v_add_f32_e32 v14, v14, v19
	s_waitcnt lgkmcnt(1)
	v_add_f32_e32 v16, v16, v20
	s_waitcnt lgkmcnt(0)
	v_add_f32_e32 v17, v17, v24
	v_cndmask_b32_e64 v19, v13, v16, s[8:9]
	v_cndmask_b32_e64 v20, v14, v17, s[8:9]
	ds_bpermute_b32 v19, v70, v19
	ds_bpermute_b32 v20, v70, v20
	v_cndmask_b32_e64 v13, v16, v13, s[8:9]
	v_cndmask_b32_e64 v14, v17, v14, s[8:9]
	s_waitcnt lgkmcnt(1)
	v_add_f32_e32 v13, v13, v19
	s_waitcnt lgkmcnt(0)
	v_add_f32_e32 v14, v14, v20
	v_cndmask_b32_e64 v16, v13, v14, s[10:11]
	ds_bpermute_b32 v16, v72, v16
	v_cndmask_b32_e64 v13, v14, v13, s[10:11]
	s_waitcnt lgkmcnt(0)
	v_add_f32_e32 v13, v13, v16
	ds_bpermute_b32 v14, v74, v13
	s_waitcnt lgkmcnt(0)
	v_add_f32_e32 v13, v13, v14
	ds_bpermute_b32 v14, v73, v13
	s_waitcnt lgkmcnt(0)
	v_add_f32_e32 v13, v13, v14
	ds_bpermute_b32 v14, v69, v13
	s_waitcnt lgkmcnt(0)
	v_max_f32_e32 v14, v14, v14
	v_max_f32_e32 v14, v13, v14
	ds_bpermute_b32 v16, v71, v14
	s_waitcnt lgkmcnt(0)
	v_max_f32_e32 v16, v16, v16
	v_max_f32_e32 v14, v14, v16
	ds_bpermute_b32 v16, v70, v14
	s_waitcnt lgkmcnt(0)
	v_max_f32_e32 v16, v16, v16
	v_max_f32_e32 v14, v14, v16
	ds_bpermute_b32 v16, v72, v14
	s_waitcnt lgkmcnt(0)
	v_max_f32_e32 v16, v16, v16
	v_max_f32_e32 v14, v14, v16
	v_sub_f32_e32 v13, v13, v14
	v_mul_f32_e32 v14, 0x3fb8aa3b, v13
	v_fma_f32 v16, v13, s20, -v14
	v_rndne_f32_e32 v17, v14
	v_fmac_f32_e32 v16, 0x32a5705f, v13
	v_sub_f32_e32 v14, v14, v17
	v_add_f32_e32 v14, v14, v16
	v_exp_f32_e32 v14, v14
	v_cvt_i32_f32_e32 v19, v17
	v_cmp_ngt_f32_e32 vcc, s21, v13
	v_lshlrev_b64 v[16:17], 10, v[54:55]
	v_lshl_add_u64 v[16:17], v[50:51], 0, v[16:17]
	v_ldexp_f32 v14, v14, v19
	v_cndmask_b32_e32 v14, 0, v14, vcc
	v_cmp_nlt_f32_e32 vcc, s22, v13
	v_mov_b32_e32 v19, 0
	v_cvt_pk_fp8_f32 v19, v18, v22
	v_cndmask_b32_e32 v13, v68, v14, vcc
	ds_bpermute_b32 v14, v69, v13
	v_mov_b32_e32 v18, 0
	v_cvt_pk_fp8_f32 v18, v2, v4
	v_cvt_pk_fp8_f32 v19, v0, v3 op_sel:[0,0,1]
	s_waitcnt lgkmcnt(0)
	v_add_f32_e32 v2, v13, v14
	ds_bpermute_b32 v4, v71, v2
	v_mov_b32_e32 v14, 0
	v_cvt_pk_fp8_f32 v14, v6, v8
	v_mov_b32_e32 v6, 0
	v_cvt_pk_fp8_f32 v6, v9, v10
	s_waitcnt lgkmcnt(0)
	v_add_f32_e32 v2, v2, v4
	ds_bpermute_b32 v4, v70, v2
	v_cvt_pk_fp8_f32 v18, v1, v7 op_sel:[0,0,1]
	v_cvt_pk_fp8_f32 v14, v5, v11 op_sel:[0,0,1]
	v_cvt_pk_fp8_f32 v6, v12, v15 op_sel:[0,0,1]
	global_store_dword v[16:17], v19, off
	global_store_dword v[16:17], v18, off offset:256
	global_store_dword v[16:17], v14, off offset:512
	global_store_dword v[16:17], v6, off offset:768
	s_waitcnt lgkmcnt(0)
	v_add_f32_e32 v0, v2, v4
	ds_bpermute_b32 v1, v72, v0
	s_and_saveexec_b64 s[16:17], s[12:13]
	s_cbranch_execz .LBB0_1071
; DEVI void ph_lnrouter(const Params& p, int layer, char* shm) {
;     ...
;       float ex = expf(v - mx);
;       float sm = ex;
;       sm += __shfl_xor(sm, 32);
;       sm += __shfl_xor(sm, 16);
;       sm += __shfl_xor(sm, 8);
;       sm += __shfl_xor(sm, 4);
;       int e = ((lane >> 5) & 1) * 8 + ((lane >> 4) & 1) * 4 + ((lane >> 3) & 1) * 2 + ((lane >> 2) & 1);
;       if ((lane & 3) == 0) aff[(size_t)tok * 16 + e] = ex / sm;
	s_waitcnt lgkmcnt(0)
	v_add_f32_e32 v0, v0, v1
	v_div_scale_f32 v1, s[24:25], v0, v0, v13
	v_rcp_f32_e32 v2, v1
	v_div_scale_f32 v3, vcc, v13, v0, v13
	v_fma_f32 v4, -v1, v2, 1.0
	v_fmac_f32_e32 v2, v4, v2
	v_mul_f32_e32 v4, v3, v2
	v_fma_f32 v5, -v1, v4, v3
	v_fmac_f32_e32 v4, v5, v2
	v_fma_f32 v1, -v1, v4, v3
	v_div_fmas_f32 v1, v1, v2, v4
	v_div_fixup_f32 v2, v1, v0, v13
	v_lshlrev_b64 v[0:1], 6, v[54:55]
	v_lshl_add_u64 v[0:1], v[52:53], 0, v[0:1]
	global_store_dword v[0:1], v2, off
	s_branch .LBB0_1071

; DEVI void ph_lnrouter(const Params& p, int layer, char* shm) {
;     ...
;   const int tid = opaque_tid(), w = tid >> 6, lane = tid & 63;
;   __syncthreads();
;   for (int i = tid; i < 4096; i += NTHR) {
;     float4 v = *reinterpret_cast<const float4*>(wrt + (size_t)i * 4);
;     int c = i >> 2, e0 = (i & 3) * 4;
;     Wt[(e0 + 0) * 1024 + c] = v.x;
;     Wt[(e0 + 1) * 1024 + c] = v.y;
;     Wt[(e0 + 2) * 1024 + c] = v.z;
;     Wt[(e0 + 3) * 1024 + c] = v.w;
;   }
;   __syncthreads();
;   for (int it = blockIdx.x; it < 4096; it += gridDim.x) {
;     asm volatile("" ::: "memory");
;     const int tok = it * 8 + w;
;     float x[16];
; #pragma unroll
;     for (int i = 0; i < 4; ++i) {
;       float4 v = *reinterpret_cast<const float4*>(h32 + (size_t)tok * 1024 + i * 256 + lane * 4);
;       x[i * 4] = v.x; x[i * 4 + 1] = v.y; x[i * 4 + 2] = v.z; x[i * 4 + 3] = v.w;
.LBB0_1905:
	s_or_b64 exec, exec, s[0:1]
	v_readlane_b32 s0, v241, 32
	v_readlane_b32 s1, v241, 33
	s_and_b64 vcc, exec, s[0:1]
	s_waitcnt lgkmcnt(0)
	s_barrier
	s_cbranch_vccnz .LBB0_1912
	s_waitcnt vmcnt(0)
	v_and_b32_e32 v6, 63, v0
	v_mov_b32_e32 v3, 0
	v_readlane_b32 s0, v242, 0
	v_lshlrev_b32_e32 v4, 4, v6
	v_mov_b32_e32 v5, v3
	v_readlane_b32 s1, v242, 1
	v_readlane_b32 s2, v242, 2
	v_readlane_b32 s3, v242, 3
	v_readlane_b32 s4, v242, 4
	v_readlane_b32 s5, v242, 5
	v_readlane_b32 s6, v242, 6
	v_readlane_b32 s7, v242, 7
	v_lshlrev_b32_e32 v2, 2, v6
	v_lshl_add_u64 v[50:51], s[76:77], 0, v[2:3]
	v_lshl_add_u64 v[44:45], s[6:7], 0, v[4:5]
	v_readlane_b32 s0, v242, 26
	v_readlane_b32 s10, v242, 36
	v_readlane_b32 s11, v242, 37
	v_and_b32_e32 v2, 16, v0
	v_readlane_b32 s12, v242, 38
	v_readlane_b32 s13, v242, 39
	v_cmp_eq_u32_e64 s[10:11], 0, v2
	v_and_b32_e32 v2, 8, v0
	v_readlane_b32 s14, v242, 40
	v_readlane_b32 s15, v242, 41
	v_cmp_eq_u32_e64 s[12:13], 0, v2
	v_and_b32_e32 v2, 4, v0
	v_cmp_eq_u32_e64 s[14:15], 0, v2
	v_and_b32_e32 v2, 3, v0
	v_mbcnt_hi_u32_b32 v59, -1, v215
	v_ashrrev_i32_e32 v1, 6, v0
	v_readlane_b32 s1, v242, 27
	v_readlane_b32 s4, v242, 30
	v_readlane_b32 s5, v242, 31
	v_readlane_b32 s6, v242, 32
	v_readlane_b32 s7, v242, 33
	v_readlane_b32 s8, v242, 34
	v_readlane_b32 s9, v242, 35
	v_cmp_eq_u32_e64 s[16:17], 0, v2
	v_and_b32_e32 v2, 60, v0
	s_add_u32 s0, s72, 0xce10000
	v_and_b32_e32 v0, 64, v59
	v_lshl_add_u64 v[46:47], s[6:7], 0, v[4:5]
	v_lshl_add_u64 v[48:49], s[8:9], 0, v[4:5]
	v_cmp_eq_u32_e64 s[6:7], 0, v6
	v_add_u32_e32 v58, 0, v4
	v_cmp_gt_u32_e64 s[8:9], 32, v6
	v_lshl_add_u64 v[52:53], s[46:47], 0, v[2:3]
	s_addc_u32 s1, s73, 0
	v_lshl_add_u32 v54, s89, 3, v1
	s_lshl_b32 s4, s78, 3
	v_add_u32_e32 v60, 64, v0
	v_xor_b32_e32 v61, 32, v59
	v_xor_b32_e32 v62, 16, v59
	v_xor_b32_e32 v63, 8, v59
	v_xor_b32_e32 v64, 4, v59
	v_xor_b32_e32 v65, 2, v59
	v_xor_b32_e32 v66, 1, v59
	v_mov_b32_e32 v67, 0x3727c5ac
	s_mov_b32 s5, 0x800000
	s_mov_b32 s18, 0x3fb8aa3b
	s_mov_b32 s19, 0xc2ce8ed0
	s_mov_b32 s20, 0x42b17218
	v_mov_b32_e32 v68, 0x7f800000
	s_mov_b32 s21, s89
	v_readlane_b32 s2, v242, 28
	v_readlane_b32 s3, v242, 29
	v_ashrrev_i32_e32 v55, 31, v54
	v_lshlrev_b64 v[116:117], 12, v[54:55]
	v_lshl_add_u64 v[116:117], v[44:45], 0, v[116:117]
	global_load_dwordx4 v[100:103], v[116:117], off
	global_load_dwordx4 v[104:107], v[116:117], off offset:1024
	global_load_dwordx4 v[108:111], v[116:117], off offset:2048
	global_load_dwordx4 v[112:115], v[116:117], off offset:3072
	s_waitcnt vmcnt(0)
	s_branch .LBB0_1908

; DEVI void ln_row(float (&x)[16], const float* __restrict__ g, const float* __restrict__ b, int lane, float* mu_out = nullptr,
;                  float* rstd_out = nullptr) {
;   float s = 0.f;
; #pragma unroll
;   for (int i = 0; i < 16; ++i) s += x[i];
;   s = wave_sum(s);
;   float mu = s * (1.0f / 1024.0f);
;   float v = 0.f;
; #pragma unroll
;   for (int i = 0; i < 16; ++i) { float d = x[i] - mu; v += d * d; }
;   v = wave_sum(v);
;   float rstd = rsqrtf(v * (1.0f / 1024.0f) + 1e-5f);
; DEVI void ph_lnrouter(const Params& p, int layer, char* shm) {
;     ...
;   for (int it = blockIdx.x; it < 4096; it += gridDim.x) {
;     asm volatile("" ::: "memory");
;     const int tok = it * 8 + w;
;     float x[16];
; #pragma unroll
;     for (int i = 0; i < 4; ++i) {
;       float4 v = *reinterpret_cast<const float4*>(h32 + (size_t)tok * 1024 + i * 256 + lane * 4);
;       x[i * 4] = v.x; x[i * 4 + 1] = v.y; x[i * 4 + 2] = v.z; x[i * 4 + 3] = v.w;
;     }
;     float mu_, rstd_;
;     ln_row(x, g, b, lane, &mu_, &rstd_);
.LBB0_1908:
	v_ashrrev_i32_e32 v55, 31, v54
	s_waitcnt lgkmcnt(0)
	v_lshlrev_b64 v[0:1], 12, v[54:55]
	v_lshl_add_u64 v[0:1], v[44:45], 0, v[0:1]
	s_waitcnt vmcnt(5)
	v_mov_b32_e32 v24, v100
	v_mov_b32_e32 v25, v101
	v_mov_b32_e32 v26, v102
	v_mov_b32_e32 v27, v103
	v_mov_b32_e32 v20, v104
	v_mov_b32_e32 v21, v105
	v_mov_b32_e32 v22, v106
	v_mov_b32_e32 v23, v107
	v_mov_b32_e32 v16, v108
	v_mov_b32_e32 v17, v109
	v_mov_b32_e32 v18, v110
	v_mov_b32_e32 v19, v111
	v_mov_b32_e32 v82, v112
	v_mov_b32_e32 v83, v113
	v_mov_b32_e32 v84, v114
	v_mov_b32_e32 v85, v115
	v_cmp_lt_i32_e32 vcc, v61, v60
	s_nop 1
	v_cndmask_b32_e32 v0, v59, v61, vcc
	v_lshlrev_b32_e32 v69, 2, v0
	v_cmp_lt_i32_e32 vcc, v62, v60
	v_add_f32_e32 v0, 0, v24
	v_add_f32_e32 v0, v25, v0
	v_add_f32_e32 v0, v26, v0
	v_add_f32_e32 v0, v27, v0
	v_add_f32_e32 v0, v20, v0
	v_add_f32_e32 v0, v21, v0
	v_add_f32_e32 v0, v22, v0
	v_add_f32_e32 v0, v23, v0
	v_add_f32_e32 v0, v16, v0
	v_add_f32_e32 v0, v17, v0
	v_add_f32_e32 v0, v18, v0
	v_add_f32_e32 v0, v19, v0
	v_add_f32_e32 v0, v82, v0
	v_add_f32_e32 v0, v83, v0
	v_add_f32_e32 v0, v84, v0
	v_add_f32_e32 v0, v85, v0
	ds_bpermute_b32 v1, v69, v0
	v_cndmask_b32_e32 v2, v59, v62, vcc
	v_lshlrev_b32_e32 v71, 2, v2
	v_cmp_lt_i32_e32 vcc, v63, v60
	s_waitcnt lgkmcnt(0)
	v_add_f32_e32 v0, v0, v1
	ds_bpermute_b32 v1, v71, v0
	v_cndmask_b32_e32 v2, v59, v63, vcc
	v_lshlrev_b32_e32 v70, 2, v2
	v_cmp_lt_i32_e32 vcc, v64, v60
	s_waitcnt lgkmcnt(0)
	v_add_f32_e32 v0, v0, v1
	ds_bpermute_b32 v1, v70, v0
	v_cndmask_b32_e32 v2, v59, v64, vcc
	v_lshlrev_b32_e32 v72, 2, v2
	v_cmp_lt_i32_e32 vcc, v65, v60
	s_waitcnt lgkmcnt(0)
	v_add_f32_e32 v0, v0, v1
	ds_bpermute_b32 v1, v72, v0
	v_cndmask_b32_e32 v3, v59, v65, vcc
	v_lshlrev_b32_e32 v74, 2, v3
	v_cmp_lt_i32_e32 vcc, v66, v60
	s_waitcnt lgkmcnt(0)
	v_add_f32_e32 v8, v0, v1
	ds_bpermute_b32 v9, v74, v8
	v_cndmask_b32_e32 v2, v59, v66, vcc
	v_lshlrev_b32_e32 v73, 2, v2
	global_load_dwordx4 v[40:43], v[46:47], off
	global_load_dwordx4 v[36:39], v[46:47], off offset:1024
	global_load_dwordx4 v[0:3], v[48:49], off
	global_load_dwordx4 v[4:7], v[48:49], off offset:1024
	s_waitcnt lgkmcnt(0)
	v_add_f32_e32 v56, v8, v9
	global_load_dwordx4 v[32:35], v[46:47], off offset:2048
	global_load_dwordx4 v[28:31], v[46:47], off offset:3072
	global_load_dwordx4 v[8:11], v[48:49], off offset:2048
	global_load_dwordx4 v[12:15], v[48:49], off offset:3072
	ds_bpermute_b32 v57, v73, v56
	s_waitcnt lgkmcnt(0)
	v_add_f32_e32 v57, v56, v57
	v_fmamk_f32 v79, v57, 0xba800000, v25
	v_fmamk_f32 v80, v57, 0xba800000, v24
	v_fmamk_f32 v24, v57, 0xba800000, v18
	v_mul_f32_e32 v18, v79, v79
	v_fmamk_f32 v78, v57, 0xba800000, v26
	v_fmac_f32_e32 v18, v80, v80
	v_fmac_f32_e32 v27, 0xba800000, v57
	v_fmac_f32_e32 v18, v78, v78
	v_fmamk_f32 v77, v57, 0xba800000, v20
	v_fmac_f32_e32 v18, v27, v27
	v_fmamk_f32 v76, v57, 0xba800000, v21
	v_fmac_f32_e32 v18, v77, v77
	v_fmamk_f32 v75, v57, 0xba800000, v22
	v_fmac_f32_e32 v18, v76, v76
	v_fmac_f32_e32 v23, 0xba800000, v57
	v_fmac_f32_e32 v18, v75, v75
	v_fmamk_f32 v26, v57, 0xba800000, v16
	v_fmac_f32_e32 v18, v23, v23
	v_fmamk_f32 v25, v57, 0xba800000, v17
	v_fmac_f32_e32 v18, v26, v26
	v_mul_f32_e32 v56, 0x3a800000, v57
	v_fmac_f32_e32 v18, v25, v25
	v_fmac_f32_e32 v19, 0xba800000, v57
	v_pk_add_f32 v[20:21], v[82:83], v[56:57] op_sel_hi:[1,0] neg_lo:[0,1] neg_hi:[0,1]
	v_fmac_f32_e32 v18, v24, v24
	v_pk_mul_f32 v[82:83], v[20:21], v[20:21]
	v_fmac_f32_e32 v18, v19, v19
	v_pk_add_f32 v[16:17], v[84:85], v[56:57] op_sel_hi:[1,0] neg_lo:[0,1] neg_hi:[0,1]
	v_add_f32_e32 v18, v82, v18
	v_pk_mul_f32 v[84:85], v[16:17], v[16:17]
	v_add_f32_e32 v18, v83, v18
	v_add_f32_e32 v18, v84, v18
	v_add_f32_e32 v18, v85, v18
	ds_bpermute_b32 v22, v69, v18
	s_waitcnt lgkmcnt(0)
	v_add_f32_e32 v18, v18, v22
	ds_bpermute_b32 v22, v71, v18
	s_waitcnt lgkmcnt(0)
	v_add_f32_e32 v18, v18, v22
	ds_bpermute_b32 v22, v70, v18
	s_waitcnt lgkmcnt(0)
	v_add_f32_e32 v18, v18, v22
	ds_bpermute_b32 v22, v72, v18
	s_waitcnt lgkmcnt(0)
	v_add_f32_e32 v18, v18, v22
	ds_bpermute_b32 v22, v74, v18
	s_waitcnt lgkmcnt(0)
	v_add_f32_e32 v18, v18, v22
	ds_bpermute_b32 v22, v73, v18
	s_waitcnt lgkmcnt(0)
	v_add_f32_e32 v18, v18, v22
	v_fmamk_f32 v18, v18, 0x3a800000, v67
	v_mul_f32_e32 v22, 0x4b800000, v18
	v_cmp_gt_f32_e32 vcc, s5, v18
	s_nop 1
	v_cndmask_b32_e32 v18, v18, v22, vcc
	v_rsq_f32_e32 v18, v18
	s_nop 0
	v_mul_f32_e32 v22, 0x45800000, v18
	v_cndmask_b32_e32 v57, v18, v22, vcc
	s_and_saveexec_b64 s[2:3], s[6:7]
	s_cbranch_execz .LBB0_1910
	v_lshl_add_u64 v[82:83], v[54:55], 3, s[0:1]
	global_store_dwordx2 v[82:83], v[56:57], off
.LBB0_1910:
	s_or_b64 exec, exec, s[2:3]
	v_mul_f32_e32 v18, v80, v57
	s_waitcnt vmcnt(5)
	v_fma_f32 v18, v40, v18, v0
	v_mul_f32_e32 v0, v79, v57
	v_fma_f32 v22, v41, v0, v1
	v_mul_f32_e32 v1, v27, v57
	v_mul_f32_e32 v0, v78, v57
	v_fmac_f32_e32 v3, v43, v1
	v_mul_f32_e32 v1, v77, v57
	v_fma_f32 v0, v42, v0, v2
	s_waitcnt vmcnt(4)
	v_fma_f32 v2, v36, v1, v4
	v_mul_f32_e32 v1, v76, v57
	v_fma_f32 v4, v37, v1, v5
	v_mul_f32_e32 v5, v23, v57
	v_mul_f32_e32 v1, v75, v57
	v_fmac_f32_e32 v7, v39, v5
	v_mul_f32_e32 v5, v26, v57
	v_fma_f32 v1, v38, v1, v6
	s_waitcnt vmcnt(1)
	v_fma_f32 v6, v32, v5, v8
	v_mul_f32_e32 v5, v25, v57
	v_fma_f32 v8, v33, v5, v9
	v_mul_f32_e32 v5, v24, v57
	ds_read_b128 v[24:27], v58
	v_mul_f32_e32 v9, v19, v57
	v_fma_f32 v5, v34, v5, v10
	v_fmac_f32_e32 v11, v35, v9
	v_mul_f32_e32 v9, v20, v57
	v_mul_f32_e32 v10, v21, v57
	s_waitcnt vmcnt(0)
	s_add_i32 s98, s21, s78
	s_cmpk_lt_i32 s98, 0x1000
	s_cbranch_scc0 .Lln1_nopf
	v_add_u32_e32 v116, s4, v54
	v_ashrrev_i32_e32 v117, 31, v116
	v_lshlrev_b64 v[116:117], 12, v[116:117]
	v_lshl_add_u64 v[116:117], v[44:45], 0, v[116:117]
	global_load_dwordx4 v[100:103], v[116:117], off
	global_load_dwordx4 v[104:107], v[116:117], off offset:1024
	global_load_dwordx4 v[108:111], v[116:117], off offset:2048
	global_load_dwordx4 v[112:115], v[116:117], off offset:3072
; DEVI void ln_row(float (&x)[16], const float* __restrict__ g, const float* __restrict__ b, int lane, float* mu_out = nullptr,
;                  float* rstd_out = nullptr) {
;     ...
;     x[i * 4 + 0] = (x[i * 4 + 0] - mu) * rstd * gg.x + bb.x;
;     x[i * 4 + 1] = (x[i * 4 + 1] - mu) * rstd * gg.y + bb.y;
;     x[i * 4 + 2] = (x[i * 4 + 2] - mu) * rstd * gg.z + bb.z;
;     x[i * 4 + 3] = (x[i * 4 + 3] - mu) * rstd * gg.w + bb.w;
; DEVI void ph_lnrouter(const Params& p, int layer, char* shm) {
;     ...
;     float le[16];
; #pragma unroll
;     for (int e = 0; e < 16; ++e) {
;       float a0 = 0.f;
; #pragma unroll
;       for (int i = 0; i < 4; ++i) {
;         float4 wv = *reinterpret_cast<const float4*>(Wt + e * 1024 + i * 256 + lane * 4);
;         a0 += x[i * 4] * wv.x + x[i * 4 + 1] * wv.y + x[i * 4 + 2] * wv.z + x[i * 4 + 3] * wv.w;
;       }
;       le[e] = a0;
;     }
.Lln1_nopf:
	v_fma_f32 v9, v28, v9, v12
	v_fma_f32 v10, v29, v10, v13
	v_mul_f32_e32 v12, v16, v57
	v_mul_f32_e32 v13, v17, v57
	v_fma_f32 v12, v30, v12, v14
	v_fmac_f32_e32 v15, v13, v31
	ds_read_b128 v[28:31], v58 offset:1024
	s_waitcnt lgkmcnt(1)
	v_mul_f32_e32 v13, v22, v25
	v_fmac_f32_e32 v13, v18, v24
	v_fmac_f32_e32 v13, v0, v26
	v_fmac_f32_e32 v13, v3, v27
	ds_read_b128 v[24:27], v58 offset:2048
	s_waitcnt lgkmcnt(1)
	v_mul_f32_e32 v14, v4, v29
	v_fmac_f32_e32 v14, v2, v28
	v_fmac_f32_e32 v14, v1, v30
	v_add_f32_e32 v13, 0, v13
	v_fmac_f32_e32 v14, v7, v31
	ds_read_b128 v[28:31], v58 offset:3072
	v_add_f32_e32 v13, v13, v14
	s_waitcnt lgkmcnt(1)
	v_mul_f32_e32 v14, v8, v25
	v_fmac_f32_e32 v14, v6, v24
	v_fmac_f32_e32 v14, v5, v26
	v_fmac_f32_e32 v14, v11, v27
	ds_read_b128 v[24:27], v58 offset:4096
	v_add_f32_e32 v13, v13, v14
	s_waitcnt lgkmcnt(1)
	v_mul_f32_e32 v14, v10, v29
	v_fmac_f32_e32 v14, v9, v28
	v_fmac_f32_e32 v14, v12, v30
	v_fmac_f32_e32 v14, v15, v31
	ds_read_b128 v[28:31], v58 offset:5120
	v_add_f32_e32 v13, v13, v14
	s_waitcnt lgkmcnt(1)
	v_mul_f32_e32 v14, v22, v25
	v_fmac_f32_e32 v14, v18, v24
	v_fmac_f32_e32 v14, v0, v26
	v_fmac_f32_e32 v14, v3, v27
	ds_read_b128 v[24:27], v58 offset:6144
	s_waitcnt lgkmcnt(1)
	v_mul_f32_e32 v16, v4, v29
	v_fmac_f32_e32 v16, v2, v28
	v_fmac_f32_e32 v16, v1, v30
	v_add_f32_e32 v14, 0, v14
	v_fmac_f32_e32 v16, v7, v31
	ds_read_b128 v[28:31], v58 offset:7168
	v_add_f32_e32 v14, v14, v16
	s_waitcnt lgkmcnt(1)
	v_mul_f32_e32 v16, v8, v25
	v_fmac_f32_e32 v16, v6, v24
	v_fmac_f32_e32 v16, v5, v26
	v_fmac_f32_e32 v16, v11, v27
	ds_read_b128 v[24:27], v58 offset:8192
	v_add_f32_e32 v14, v14, v16
	s_waitcnt lgkmcnt(1)
	v_mul_f32_e32 v16, v10, v29
	v_fmac_f32_e32 v16, v9, v28
	v_fmac_f32_e32 v16, v12, v30
	v_fmac_f32_e32 v16, v15, v31
	ds_read_b128 v[28:31], v58 offset:9216
	v_add_f32_e32 v14, v14, v16
	s_waitcnt lgkmcnt(1)
	v_mul_f32_e32 v16, v22, v25
	v_fmac_f32_e32 v16, v18, v24
	v_fmac_f32_e32 v16, v0, v26
	v_fmac_f32_e32 v16, v3, v27
	ds_read_b128 v[24:27], v58 offset:10240
	s_waitcnt lgkmcnt(1)
	v_mul_f32_e32 v17, v4, v29
	v_fmac_f32_e32 v17, v2, v28
	v_fmac_f32_e32 v17, v1, v30
	v_add_f32_e32 v16, 0, v16
	v_fmac_f32_e32 v17, v7, v31
	ds_read_b128 v[28:31], v58 offset:11264
	v_add_f32_e32 v16, v16, v17
	s_waitcnt lgkmcnt(1)
	v_mul_f32_e32 v17, v8, v25
	v_fmac_f32_e32 v17, v6, v24
	v_fmac_f32_e32 v17, v5, v26
	v_fmac_f32_e32 v17, v11, v27
	ds_read_b128 v[24:27], v58 offset:12288
	v_add_f32_e32 v16, v16, v17
	s_waitcnt lgkmcnt(1)
	v_mul_f32_e32 v17, v10, v29
	v_fmac_f32_e32 v17, v9, v28
	v_fmac_f32_e32 v17, v12, v30
	v_fmac_f32_e32 v17, v15, v31
	ds_read_b128 v[28:31], v58 offset:13312
	v_add_f32_e32 v16, v16, v17
	s_waitcnt lgkmcnt(1)
	v_mul_f32_e32 v17, v22, v25
	v_fmac_f32_e32 v17, v18, v24
	v_fmac_f32_e32 v17, v0, v26
	v_fmac_f32_e32 v17, v3, v27
	ds_read_b128 v[24:27], v58 offset:14336
	s_waitcnt lgkmcnt(1)
	v_mul_f32_e32 v19, v4, v29
	v_fmac_f32_e32 v19, v2, v28
	v_fmac_f32_e32 v19, v1, v30
	v_add_f32_e32 v17, 0, v17
	v_fmac_f32_e32 v19, v7, v31
	ds_read_b128 v[28:31], v58 offset:15360
	v_add_f32_e32 v17, v17, v19
	s_waitcnt lgkmcnt(1)
	v_mul_f32_e32 v19, v8, v25
	v_fmac_f32_e32 v19, v6, v24
	v_fmac_f32_e32 v19, v5, v26
	v_fmac_f32_e32 v19, v11, v27
	ds_read_b128 v[24:27], v58 offset:16384
	v_add_f32_e32 v17, v17, v19
	s_waitcnt lgkmcnt(1)
	v_mul_f32_e32 v19, v10, v29
	v_fmac_f32_e32 v19, v9, v28
	v_fmac_f32_e32 v19, v12, v30
	v_fmac_f32_e32 v19, v15, v31
	ds_read_b128 v[28:31], v58 offset:17408
	v_add_f32_e32 v17, v17, v19
	s_waitcnt lgkmcnt(1)
	v_mul_f32_e32 v19, v22, v25
	v_fmac_f32_e32 v19, v18, v24
	v_fmac_f32_e32 v19, v0, v26
	v_fmac_f32_e32 v19, v3, v27
	ds_read_b128 v[24:27], v58 offset:18432
	s_waitcnt lgkmcnt(1)
	v_mul_f32_e32 v20, v4, v29
	v_fmac_f32_e32 v20, v2, v28
	v_fmac_f32_e32 v20, v1, v30
	v_add_f32_e32 v19, 0, v19
	v_fmac_f32_e32 v20, v7, v31
	ds_read_b128 v[28:31], v58 offset:19456
	v_add_f32_e32 v19, v19, v20
	s_waitcnt lgkmcnt(1)
	v_mul_f32_e32 v20, v8, v25
	v_fmac_f32_e32 v20, v6, v24
	v_fmac_f32_e32 v20, v5, v26
	v_fmac_f32_e32 v20, v11, v27
	ds_read_b128 v[24:27], v58 offset:20480
	v_add_f32_e32 v19, v19, v20
	s_waitcnt lgkmcnt(1)
	v_mul_f32_e32 v20, v10, v29
	v_fmac_f32_e32 v20, v9, v28
	v_fmac_f32_e32 v20, v12, v30
	v_fmac_f32_e32 v20, v15, v31
	ds_read_b128 v[28:31], v58 offset:21504
	v_add_f32_e32 v19, v19, v20
	s_waitcnt lgkmcnt(1)
	v_mul_f32_e32 v20, v22, v25
	v_fmac_f32_e32 v20, v18, v24
	v_fmac_f32_e32 v20, v0, v26
	v_fmac_f32_e32 v20, v3, v27
	ds_read_b128 v[24:27], v58 offset:22528
	s_waitcnt lgkmcnt(1)
	v_mul_f32_e32 v21, v4, v29
	v_fmac_f32_e32 v21, v2, v28
	v_fmac_f32_e32 v21, v1, v30
	v_add_f32_e32 v20, 0, v20
	v_fmac_f32_e32 v21, v7, v31
	ds_read_b128 v[28:31], v58 offset:23552
	v_add_f32_e32 v20, v20, v21
	s_waitcnt lgkmcnt(1)
	v_mul_f32_e32 v21, v8, v25
	v_fmac_f32_e32 v21, v6, v24
	v_fmac_f32_e32 v21, v5, v26
	v_fmac_f32_e32 v21, v11, v27
	ds_read_b128 v[24:27], v58 offset:24576
	v_add_f32_e32 v20, v20, v21
	s_waitcnt lgkmcnt(1)
	v_mul_f32_e32 v21, v10, v29
	v_fmac_f32_e32 v21, v9, v28
	v_fmac_f32_e32 v21, v12, v30
	v_fmac_f32_e32 v21, v15, v31
	ds_read_b128 v[28:31], v58 offset:25600
	v_add_f32_e32 v20, v20, v21
	s_waitcnt lgkmcnt(1)
	v_mul_f32_e32 v21, v22, v25
	v_fmac_f32_e32 v21, v18, v24
	v_fmac_f32_e32 v21, v0, v26
	v_fmac_f32_e32 v21, v3, v27
	ds_read_b128 v[24:27], v58 offset:26624
	s_waitcnt lgkmcnt(1)
	v_mul_f32_e32 v23, v4, v29
	v_fmac_f32_e32 v23, v2, v28
	v_fmac_f32_e32 v23, v1, v30
	v_add_f32_e32 v21, 0, v21
	v_fmac_f32_e32 v23, v7, v31
	ds_read_b128 v[28:31], v58 offset:27648
	v_add_f32_e32 v21, v21, v23
	s_waitcnt lgkmcnt(1)
; DEVI void ph_lnrouter(const Params& p, int layer, char* shm) {
;     ...
;     float le[16];
; #pragma unroll
;     for (int e = 0; e < 16; ++e) {
;       float a0 = 0.f;
; #pragma unroll
;       for (int i = 0; i < 4; ++i) {
;         float4 wv = *reinterpret_cast<const float4*>(Wt + e * 1024 + i * 256 + lane * 4);
;         a0 += x[i * 4] * wv.x + x[i * 4 + 1] * wv.y + x[i * 4 + 2] * wv.z + x[i * 4 + 3] * wv.w;
;       }
;       le[e] = a0;
;     }
	v_mul_f32_e32 v23, v8, v25
	v_fmac_f32_e32 v23, v6, v24
	v_fmac_f32_e32 v23, v5, v26
	v_fmac_f32_e32 v23, v11, v27
	v_add_f32_e32 v21, v21, v23
	s_waitcnt lgkmcnt(0)
	v_mul_f32_e32 v23, v10, v29
	ds_read_b128 v[24:27], v58 offset:28672
	v_fmac_f32_e32 v23, v9, v28
	v_fmac_f32_e32 v23, v12, v30
	v_fmac_f32_e32 v23, v15, v31
	ds_read_b128 v[28:31], v58 offset:29696
	v_add_f32_e32 v21, v21, v23
	s_waitcnt lgkmcnt(1)
	v_mul_f32_e32 v23, v22, v25
	v_fmac_f32_e32 v23, v18, v24
	v_fmac_f32_e32 v23, v0, v26
	v_fmac_f32_e32 v23, v3, v27
	s_waitcnt lgkmcnt(0)
	v_mul_f32_e32 v29, v4, v29
	ds_read_b128 v[24:27], v58 offset:30720
	v_fmac_f32_e32 v29, v2, v28
	v_fmac_f32_e32 v29, v1, v30
	v_add_f32_e32 v23, 0, v23
	v_fmac_f32_e32 v29, v7, v31
	v_add_f32_e32 v23, v23, v29
	ds_read_b128 v[28:31], v58 offset:31744
	s_waitcnt lgkmcnt(1)
	v_mul_f32_e32 v25, v8, v25
	v_fmac_f32_e32 v25, v6, v24
	v_fmac_f32_e32 v25, v5, v26
	v_fmac_f32_e32 v25, v11, v27
	v_add_f32_e32 v23, v23, v25
	s_waitcnt lgkmcnt(0)
	v_mul_f32_e32 v29, v10, v29
	ds_read_b128 v[24:27], v58 offset:32768
	v_fmac_f32_e32 v29, v9, v28
	v_fmac_f32_e32 v29, v12, v30
	v_fmac_f32_e32 v29, v15, v31
	v_add_f32_e32 v23, v23, v29
	ds_read_b128 v[28:31], v58 offset:33792
	s_waitcnt lgkmcnt(1)
	v_mul_f32_e32 v25, v22, v25
	v_fmac_f32_e32 v25, v18, v24
	v_fmac_f32_e32 v25, v0, v26
	v_fmac_f32_e32 v25, v3, v27
	v_add_f32_e32 v32, 0, v25
	s_waitcnt lgkmcnt(0)
	v_mul_f32_e32 v29, v4, v29
	ds_read_b128 v[24:27], v58 offset:34816
	v_fmac_f32_e32 v29, v2, v28
	v_fmac_f32_e32 v29, v1, v30
	v_fmac_f32_e32 v29, v7, v31
	v_add_f32_e32 v32, v32, v29
	ds_read_b128 v[28:31], v58 offset:35840
	s_waitcnt lgkmcnt(1)
	v_mul_f32_e32 v25, v8, v25
	v_fmac_f32_e32 v25, v6, v24
	v_fmac_f32_e32 v25, v5, v26
	v_fmac_f32_e32 v25, v11, v27
	v_add_f32_e32 v32, v32, v25
	s_waitcnt lgkmcnt(0)
	v_mul_f32_e32 v29, v10, v29
	ds_read_b128 v[24:27], v58 offset:36864
	v_fmac_f32_e32 v29, v9, v28
	v_fmac_f32_e32 v29, v12, v30
	v_fmac_f32_e32 v29, v15, v31
	v_add_f32_e32 v32, v32, v29
	ds_read_b128 v[28:31], v58 offset:37888
	s_waitcnt lgkmcnt(1)
	v_mul_f32_e32 v25, v22, v25
	v_fmac_f32_e32 v25, v18, v24
	v_fmac_f32_e32 v25, v0, v26
	v_fmac_f32_e32 v25, v3, v27
	v_add_f32_e32 v33, 0, v25
	s_waitcnt lgkmcnt(0)
	v_mul_f32_e32 v29, v4, v29
	ds_read_b128 v[24:27], v58 offset:38912
	v_fmac_f32_e32 v29, v2, v28
	v_fmac_f32_e32 v29, v1, v30
	v_fmac_f32_e32 v29, v7, v31
	v_add_f32_e32 v33, v33, v29
	ds_read_b128 v[28:31], v58 offset:39936
	s_waitcnt lgkmcnt(1)
	v_mul_f32_e32 v25, v8, v25
	v_fmac_f32_e32 v25, v6, v24
	v_fmac_f32_e32 v25, v5, v26
	v_fmac_f32_e32 v25, v11, v27
	v_add_f32_e32 v33, v33, v25
	s_waitcnt lgkmcnt(0)
	v_mul_f32_e32 v29, v10, v29
	ds_read_b128 v[24:27], v58 offset:40960
	v_fmac_f32_e32 v29, v9, v28
	v_fmac_f32_e32 v29, v12, v30
	v_fmac_f32_e32 v29, v15, v31
	v_add_f32_e32 v33, v33, v29
	ds_read_b128 v[28:31], v58 offset:41984
	s_waitcnt lgkmcnt(1)
	v_mul_f32_e32 v25, v22, v25
	v_fmac_f32_e32 v25, v18, v24
	v_fmac_f32_e32 v25, v0, v26
	v_fmac_f32_e32 v25, v3, v27
	v_add_f32_e32 v34, 0, v25
	s_waitcnt lgkmcnt(0)
	v_mul_f32_e32 v29, v4, v29
	ds_read_b128 v[24:27], v58 offset:43008
	v_fmac_f32_e32 v29, v2, v28
	v_fmac_f32_e32 v29, v1, v30
	v_fmac_f32_e32 v29, v7, v31
	v_add_f32_e32 v34, v34, v29
	ds_read_b128 v[28:31], v58 offset:44032
	s_waitcnt lgkmcnt(1)
	v_mul_f32_e32 v25, v8, v25
	v_fmac_f32_e32 v25, v6, v24
	v_fmac_f32_e32 v25, v5, v26
	v_fmac_f32_e32 v25, v11, v27
	v_add_f32_e32 v34, v34, v25
	s_waitcnt lgkmcnt(0)
	v_mul_f32_e32 v29, v10, v29
	ds_read_b128 v[24:27], v58 offset:45056
	v_fmac_f32_e32 v29, v9, v28
	v_fmac_f32_e32 v29, v12, v30
	v_fmac_f32_e32 v29, v15, v31
	v_add_f32_e32 v34, v34, v29
	ds_read_b128 v[28:31], v58 offset:46080
	s_waitcnt lgkmcnt(1)
	v_mul_f32_e32 v25, v22, v25
	v_fmac_f32_e32 v25, v18, v24
	v_fmac_f32_e32 v25, v0, v26
	v_fmac_f32_e32 v25, v3, v27
	v_add_f32_e32 v35, 0, v25
	s_waitcnt lgkmcnt(0)
	v_mul_f32_e32 v29, v4, v29
	ds_read_b128 v[24:27], v58 offset:47104
	v_fmac_f32_e32 v29, v2, v28
	v_fmac_f32_e32 v29, v1, v30
	v_fmac_f32_e32 v29, v7, v31
	v_add_f32_e32 v35, v35, v29
	ds_read_b128 v[28:31], v58 offset:48128
	s_waitcnt lgkmcnt(1)
	v_mul_f32_e32 v25, v8, v25
	v_fmac_f32_e32 v25, v6, v24
	v_fmac_f32_e32 v25, v5, v26
	v_fmac_f32_e32 v25, v11, v27
	v_add_f32_e32 v35, v35, v25
	s_waitcnt lgkmcnt(0)
	v_mul_f32_e32 v29, v10, v29
	ds_read_b128 v[24:27], v58 offset:49152
	v_fmac_f32_e32 v29, v9, v28
	v_fmac_f32_e32 v29, v12, v30
	v_fmac_f32_e32 v29, v15, v31
	v_add_f32_e32 v35, v35, v29
	ds_read_b128 v[28:31], v58 offset:50176
	s_waitcnt lgkmcnt(1)
	v_mul_f32_e32 v25, v22, v25
	v_fmac_f32_e32 v25, v18, v24
	v_fmac_f32_e32 v25, v0, v26
	v_fmac_f32_e32 v25, v3, v27
	v_add_f32_e32 v36, 0, v25
	s_waitcnt lgkmcnt(0)
	v_mul_f32_e32 v29, v4, v29
	ds_read_b128 v[24:27], v58 offset:51200
	v_fmac_f32_e32 v29, v2, v28
	v_fmac_f32_e32 v29, v1, v30
	v_fmac_f32_e32 v29, v7, v31
	v_add_f32_e32 v36, v36, v29
	ds_read_b128 v[28:31], v58 offset:52224
	s_waitcnt lgkmcnt(1)
	v_mul_f32_e32 v25, v8, v25
	v_fmac_f32_e32 v25, v6, v24
	v_fmac_f32_e32 v25, v5, v26
	v_fmac_f32_e32 v25, v11, v27
	v_add_f32_e32 v36, v36, v25
	s_waitcnt lgkmcnt(0)
	v_mul_f32_e32 v29, v10, v29
	ds_read_b128 v[24:27], v58 offset:53248
	v_fmac_f32_e32 v29, v9, v28
	v_fmac_f32_e32 v29, v12, v30
	v_fmac_f32_e32 v29, v15, v31
	v_add_f32_e32 v36, v36, v29
	ds_read_b128 v[28:31], v58 offset:54272
	s_waitcnt lgkmcnt(1)
	v_mul_f32_e32 v25, v22, v25
	v_fmac_f32_e32 v25, v18, v24
	v_fmac_f32_e32 v25, v0, v26
	v_fmac_f32_e32 v25, v3, v27
	v_add_f32_e32 v37, 0, v25
	s_waitcnt lgkmcnt(0)
; DEVI float reduce16(float (&v)[16], int lane) {
;   {
;     bool up = (lane & 32) != 0;
; #pragma unroll
;     for (int k = 0; k < 8; ++k) {
;       float send = up ? v[k] : v[k + 8];
;       float keep = up ? v[k + 8] : v[k];
;       v[k] = keep + __shfl_xor(send, 32);
;     }
;   }
;   {
;     bool up = (lane & 16) != 0;
; #pragma unroll
;     for (int k = 0; k < 4; ++k) {
;       float send = up ? v[k] : v[k + 4];
;       float keep = up ? v[k + 4] : v[k];
;       v[k] = keep + __shfl_xor(send, 16);
;     }
;   }
;   {
;     bool up = (lane & 8) != 0;
; #pragma unroll
;     for (int k = 0; k < 2; ++k) {
;       float send = up ? v[k] : v[k + 2];
;       float keep = up ? v[k + 2] : v[k];
;       v[k] = keep + __shfl_xor(send, 8);
;     }
;   }
;   {
;     bool up = (lane & 4) != 0;
;     float send = up ? v[0] : v[1];
;     float keep = up ? v[1] : v[0];
;     v[0] = keep + __shfl_xor(send, 4);
;   }
;   float r = v[0];
;   r += __shfl_xor(r, 2);
;   r += __shfl_xor(r, 1);
;   return r;
; }
; DEVI void ph_lnrouter(const Params& p, int layer, char* shm) {
;     ...
;       float v = reduce16(le, lane);
;       float mx = v;
;       mx = fmaxf(mx, __shfl_xor(mx, 32));
;       mx = fmaxf(mx, __shfl_xor(mx, 16));
;       mx = fmaxf(mx, __shfl_xor(mx, 8));
;       mx = fmaxf(mx, __shfl_xor(mx, 4));
;       float ex = expf(v - mx);
;       float sm = ex;
;       sm += __shfl_xor(sm, 32);
;       sm += __shfl_xor(sm, 16);
;       sm += __shfl_xor(sm, 8);
;       sm += __shfl_xor(sm, 4);
;       int e = ((lane >> 5) & 1) * 8 + ((lane >> 4) & 1) * 4 + ((lane >> 3) & 1) * 2 + ((lane >> 2) & 1);
;       if ((lane & 3) == 0) aff[(size_t)tok * 16 + e] = ex / sm;
	v_mul_f32_e32 v29, v4, v29
	ds_read_b128 v[24:27], v58 offset:55296
	v_fmac_f32_e32 v29, v2, v28
	v_fmac_f32_e32 v29, v1, v30
	v_fmac_f32_e32 v29, v7, v31
	v_add_f32_e32 v37, v37, v29
	ds_read_b128 v[28:31], v58 offset:56320
	s_waitcnt lgkmcnt(1)
	v_mul_f32_e32 v25, v8, v25
	v_fmac_f32_e32 v25, v6, v24
	v_fmac_f32_e32 v25, v5, v26
	v_fmac_f32_e32 v25, v11, v27
	v_add_f32_e32 v37, v37, v25
	s_waitcnt lgkmcnt(0)
	v_mul_f32_e32 v29, v10, v29
	ds_read_b128 v[24:27], v58 offset:57344
	v_fmac_f32_e32 v29, v9, v28
	v_fmac_f32_e32 v29, v12, v30
	v_fmac_f32_e32 v29, v15, v31
	v_add_f32_e32 v37, v37, v29
	ds_read_b128 v[28:31], v58 offset:58368
	s_waitcnt lgkmcnt(1)
	v_mul_f32_e32 v25, v22, v25
	v_fmac_f32_e32 v25, v18, v24
	v_fmac_f32_e32 v25, v0, v26
	v_fmac_f32_e32 v25, v3, v27
	v_add_f32_e32 v38, 0, v25
	s_waitcnt lgkmcnt(0)
	v_mul_f32_e32 v29, v4, v29
	ds_read_b128 v[24:27], v58 offset:59392
	v_fmac_f32_e32 v29, v2, v28
	v_fmac_f32_e32 v29, v1, v30
	v_fmac_f32_e32 v29, v7, v31
	v_add_f32_e32 v38, v38, v29
	ds_read_b128 v[28:31], v58 offset:60416
	s_waitcnt lgkmcnt(1)
	v_mul_f32_e32 v25, v8, v25
	v_fmac_f32_e32 v25, v6, v24
	v_fmac_f32_e32 v25, v5, v26
	v_fmac_f32_e32 v25, v11, v27
	v_add_f32_e32 v38, v38, v25
	s_waitcnt lgkmcnt(0)
	v_mul_f32_e32 v29, v10, v29
	ds_read_b128 v[24:27], v58 offset:61440
	v_fmac_f32_e32 v29, v9, v28
	v_fmac_f32_e32 v29, v12, v30
	v_fmac_f32_e32 v29, v15, v31
	v_add_f32_e32 v38, v38, v29
	ds_read_b128 v[28:31], v58 offset:62464
	s_waitcnt lgkmcnt(1)
	v_mul_f32_e32 v25, v22, v25
	v_fmac_f32_e32 v25, v18, v24
	v_fmac_f32_e32 v25, v0, v26
	v_fmac_f32_e32 v25, v3, v27
	v_add_f32_e32 v39, 0, v25
	s_waitcnt lgkmcnt(0)
	v_mul_f32_e32 v29, v4, v29
	ds_read_b128 v[24:27], v58 offset:63488
	v_fmac_f32_e32 v29, v2, v28
	v_fmac_f32_e32 v29, v1, v30
	v_fmac_f32_e32 v29, v7, v31
	v_add_f32_e32 v39, v39, v29
	ds_read_b128 v[28:31], v58 offset:64512
	s_waitcnt lgkmcnt(1)
	v_mul_f32_e32 v25, v8, v25
	v_fmac_f32_e32 v25, v6, v24
	v_fmac_f32_e32 v25, v5, v26
	v_fmac_f32_e32 v25, v11, v27
	v_add_f32_e32 v24, v39, v25
	s_waitcnt lgkmcnt(0)
	v_mul_f32_e32 v25, v10, v29
	v_fmac_f32_e32 v25, v9, v28
	v_fmac_f32_e32 v25, v12, v30
	v_fmac_f32_e32 v25, v15, v31
	v_add_f32_e32 v24, v24, v25
	v_cndmask_b32_e64 v25, v13, v32, s[8:9]
	v_cndmask_b32_e64 v26, v14, v33, s[8:9]
	ds_bpermute_b32 v25, v69, v25
	ds_bpermute_b32 v26, v69, v26
	v_cndmask_b32_e64 v13, v32, v13, s[8:9]
	v_cndmask_b32_e64 v14, v33, v14, s[8:9]
	v_cndmask_b32_e64 v27, v16, v34, s[8:9]
	s_waitcnt lgkmcnt(1)
	v_add_f32_e32 v13, v13, v25
	s_waitcnt lgkmcnt(0)
	v_add_f32_e32 v14, v14, v26
	v_cndmask_b32_e64 v25, v17, v35, s[8:9]
	v_cndmask_b32_e64 v26, v19, v36, s[8:9]
	ds_bpermute_b32 v27, v69, v27
	ds_bpermute_b32 v25, v69, v25
	ds_bpermute_b32 v26, v69, v26
	v_cndmask_b32_e64 v16, v34, v16, s[8:9]
	v_cndmask_b32_e64 v17, v35, v17, s[8:9]
	v_cndmask_b32_e64 v19, v36, v19, s[8:9]
	s_waitcnt lgkmcnt(2)
	v_add_f32_e32 v16, v16, v27
	v_cndmask_b32_e64 v27, v20, v37, s[8:9]
	s_waitcnt lgkmcnt(1)
	v_add_f32_e32 v17, v17, v25
	s_waitcnt lgkmcnt(0)
	v_add_f32_e32 v19, v19, v26
	v_cndmask_b32_e64 v25, v21, v38, s[8:9]
	v_cndmask_b32_e64 v26, v23, v24, s[8:9]
	ds_bpermute_b32 v27, v69, v27
	ds_bpermute_b32 v25, v69, v25
	ds_bpermute_b32 v26, v69, v26
	v_cndmask_b32_e64 v20, v37, v20, s[8:9]
	v_cndmask_b32_e64 v21, v38, v21, s[8:9]
	v_cndmask_b32_e64 v23, v24, v23, s[8:9]
	s_waitcnt lgkmcnt(2)
	v_add_f32_e32 v20, v20, v27
	s_waitcnt lgkmcnt(1)
	v_add_f32_e32 v21, v21, v25
	s_waitcnt lgkmcnt(0)
	v_add_f32_e32 v23, v23, v26
	v_cndmask_b32_e64 v27, v13, v19, s[10:11]
	v_cndmask_b32_e64 v13, v19, v13, s[10:11]
	v_cndmask_b32_e64 v19, v14, v20, s[10:11]
	v_cndmask_b32_e64 v14, v20, v14, s[10:11]
	v_cndmask_b32_e64 v20, v16, v21, s[10:11]
	v_cndmask_b32_e64 v24, v17, v23, s[10:11]
	ds_bpermute_b32 v27, v71, v27
	ds_bpermute_b32 v19, v71, v19
	ds_bpermute_b32 v20, v71, v20
	ds_bpermute_b32 v24, v71, v24
	v_cndmask_b32_e64 v16, v21, v16, s[10:11]
	v_cndmask_b32_e64 v17, v23, v17, s[10:11]
	s_waitcnt lgkmcnt(3)
	v_add_f32_e32 v13, v13, v27
	s_waitcnt lgkmcnt(2)
	v_add_f32_e32 v14, v14, v19
	s_waitcnt lgkmcnt(1)
	v_add_f32_e32 v16, v16, v20
	s_waitcnt lgkmcnt(0)
	v_add_f32_e32 v17, v17, v24
	v_cndmask_b32_e64 v19, v13, v16, s[12:13]
	v_cndmask_b32_e64 v20, v14, v17, s[12:13]
	ds_bpermute_b32 v19, v70, v19
	ds_bpermute_b32 v20, v70, v20
	v_cndmask_b32_e64 v13, v16, v13, s[12:13]
	v_cndmask_b32_e64 v14, v17, v14, s[12:13]
	s_waitcnt lgkmcnt(1)
	v_add_f32_e32 v13, v13, v19
	s_waitcnt lgkmcnt(0)
	v_add_f32_e32 v14, v14, v20
	v_cndmask_b32_e64 v16, v13, v14, s[14:15]
	ds_bpermute_b32 v16, v72, v16
	v_cndmask_b32_e64 v13, v14, v13, s[14:15]
	s_waitcnt lgkmcnt(0)
	v_add_f32_e32 v13, v13, v16
	ds_bpermute_b32 v14, v74, v13
	s_waitcnt lgkmcnt(0)
	v_add_f32_e32 v13, v13, v14
	ds_bpermute_b32 v14, v73, v13
	s_waitcnt lgkmcnt(0)
	v_add_f32_e32 v13, v13, v14
	ds_bpermute_b32 v14, v69, v13
	s_waitcnt lgkmcnt(0)
	v_max_f32_e32 v14, v14, v14
	v_max_f32_e32 v14, v13, v14
	ds_bpermute_b32 v16, v71, v14
	s_waitcnt lgkmcnt(0)
	v_max_f32_e32 v16, v16, v16
	v_max_f32_e32 v14, v14, v16
	ds_bpermute_b32 v16, v70, v14
	s_waitcnt lgkmcnt(0)
	v_max_f32_e32 v16, v16, v16
	v_max_f32_e32 v14, v14, v16
	ds_bpermute_b32 v16, v72, v14
	s_waitcnt lgkmcnt(0)
	v_max_f32_e32 v16, v16, v16
	v_max_f32_e32 v14, v14, v16
	v_sub_f32_e32 v13, v13, v14
	v_mul_f32_e32 v14, 0x3fb8aa3b, v13
	v_fma_f32 v16, v13, s18, -v14
	v_rndne_f32_e32 v17, v14
	v_fmac_f32_e32 v16, 0x32a5705f, v13
	v_sub_f32_e32 v14, v14, v17
	v_add_f32_e32 v14, v14, v16
	v_exp_f32_e32 v14, v14
	v_cvt_i32_f32_e32 v19, v17
	v_cmp_ngt_f32_e32 vcc, s19, v13
	v_lshlrev_b64 v[16:17], 10, v[54:55]
	v_lshl_add_u64 v[16:17], v[50:51], 0, v[16:17]
	v_ldexp_f32 v14, v14, v19
	v_cndmask_b32_e32 v14, 0, v14, vcc
	v_cmp_nlt_f32_e32 vcc, s20, v13
	v_mov_b32_e32 v19, 0
	v_cvt_pk_fp8_f32 v19, v18, v22
	v_cndmask_b32_e32 v13, v68, v14, vcc
	ds_bpermute_b32 v14, v69, v13
	v_mov_b32_e32 v18, 0
	v_cvt_pk_fp8_f32 v18, v2, v4
	v_cvt_pk_fp8_f32 v19, v0, v3 op_sel:[0,0,1]
	s_waitcnt lgkmcnt(0)
	v_add_f32_e32 v2, v13, v14
	ds_bpermute_b32 v4, v71, v2
	v_mov_b32_e32 v14, 0
	v_cvt_pk_fp8_f32 v14, v6, v8
	v_mov_b32_e32 v6, 0
	v_cvt_pk_fp8_f32 v6, v9, v10
	s_waitcnt lgkmcnt(0)
	v_add_f32_e32 v2, v2, v4
	ds_bpermute_b32 v4, v70, v2
	v_cvt_pk_fp8_f32 v18, v1, v7 op_sel:[0,0,1]
	v_cvt_pk_fp8_f32 v14, v5, v11 op_sel:[0,0,1]
	v_cvt_pk_fp8_f32 v6, v12, v15 op_sel:[0,0,1]
	global_store_dword v[16:17], v19, off
	global_store_dword v[16:17], v18, off offset:256
	global_store_dword v[16:17], v14, off offset:512
	global_store_dword v[16:17], v6, off offset:768
	s_waitcnt lgkmcnt(0)
	v_add_f32_e32 v0, v2, v4
	ds_bpermute_b32 v1, v72, v0
	s_and_saveexec_b64 s[2:3], s[16:17]
	s_cbranch_execz .LBB0_1907
; DEVI void ph_lnrouter(const Params& p, int layer, char* shm) {
;     ...
;       float ex = expf(v - mx);
;       float sm = ex;
;       sm += __shfl_xor(sm, 32);
;       sm += __shfl_xor(sm, 16);
;       sm += __shfl_xor(sm, 8);
;       sm += __shfl_xor(sm, 4);
;       int e = ((lane >> 5) & 1) * 8 + ((lane >> 4) & 1) * 4 + ((lane >> 3) & 1) * 2 + ((lane >> 2) & 1);
;       if ((lane & 3) == 0) aff[(size_t)tok * 16 + e] = ex / sm;
	s_waitcnt lgkmcnt(0)
	v_add_f32_e32 v0, v0, v1
	v_div_scale_f32 v1, s[22:23], v0, v0, v13
	v_rcp_f32_e32 v2, v1
	v_div_scale_f32 v3, vcc, v13, v0, v13
	v_fma_f32 v4, -v1, v2, 1.0
	v_fmac_f32_e32 v2, v4, v2
	v_mul_f32_e32 v4, v3, v2
	v_fma_f32 v5, -v1, v4, v3
	v_fmac_f32_e32 v4, v5, v2
	v_fma_f32 v1, -v1, v4, v3
	v_div_fmas_f32 v1, v1, v2, v4
	v_div_fixup_f32 v2, v1, v0, v13
	v_lshlrev_b64 v[0:1], 6, v[54:55]
	v_lshl_add_u64 v[0:1], v[52:53], 0, v[0:1]
	global_store_dword v[0:1], v2, off
	s_branch .LBB0_1907
